# v16 + in_proj/ff13 K-loops: B-fragment LDS reads of phases 1/5 hoisted into the preceding MMA segment (LDS idle there), fixed LDS base + ds offsets, extra counted vmcnt(8); dtype comment added
# baseline (speedup 1.0000x reference)
; #define PG8_STAGE(bufoff, gbase, voff) do { _Pragma("unroll") for (int _i = 0; _i < 2; ++_i) \
;         __builtin_amdgcn_global_load_lds((const unsigned*)((const char*)(gbase) + (voff)[_i]), (LAS unsigned*)(lds + (bufoff) + ldsw + _i * 8192), 16, 0, 0); } while (0)
; #define PG8_LDA(dst, b, h) do { _Pragma("unroll") for (int m = 0; m < 4; ++m) _Pragma("unroll") for (int k = 0; k < 2; ++k) dst[m][k] = *(const LAS bf16x8*)(lds + PG8_SA(b, h) + aoff + m * 2048 + k * 1024); } while (0)
; #define PG8_LDB(dst, b, h) do { _Pragma("unroll") for (int n = 0; n < 2; ++n) _Pragma("unroll") for (int k = 0; k < 2; ++k) dst[n][k] = *(const LAS bf16x8*)(lds + PG8_SB(b, h) + boff + n * 2048 + k * 1024); } while (0)
; #define PG8_MMA(ai, bj, At, Bt) do { __builtin_amdgcn_s_setprio(1); _Pragma("unroll") for (int m = 0; m < 4; ++m) _Pragma("unroll") for (int n = 0; n < 2; ++n) _Pragma("unroll") for (int k = 0; k < 2; ++k) \
;         acc[ai][bj][m][n] = __builtin_amdgcn_mfma_f32_16x16x32_bf16(Bt[n][k], At[m][k], acc[ai][bj][m][n], 0, 0, 0); __builtin_amdgcn_s_setprio(0); } while (0)
; template <class Epi>
; __device__ __forceinline__ void gemm_phase(LAS unsigned char* lds, const Gemm g, const StaticOrder& S, const Epi& E) {
;     ...
;         const bool has_next = S.next(ui + 1, nxt);
;         const char* nA = has_next ? (const char*)(nxt.alt ? g.A2 : g.A) + (size_t)nxt.pm * tA + (size_t)nxt.k0 * 2 : cA; const char* nB = has_next ? (const char*)(nxt.alt ? g.Bt2 : g.Bt) + (size_t)nxt.pn * tB + (size_t)nxt.k0 * 2 : cB;
;         const int nt = cur.nt;
;         for (int t = 0; t < nt; t += 2) {
;             const bool last = (t == nt - 2);
;             const char* a1 = cA + (size_t)(t + 1) * kstep;
;             const char* a2 = last ? nA : cA + (size_t)(t + 2) * kstep; const char* b2 = last ? nB : cB + (size_t)(t + 2) * kstep;
;             const char* a3 = a2 + kstep; const char* b3 = b2 + kstep;
;             PG8_LDB(B0, 0, 0); PG8_SCHED; PG8_LDA(At, 0, 0); PG8_STAGE(PG8_SA(1, 1), a1 + hA, voffA);
;             PG8_WAIT_L(8); PG8_BAR; PG8_WAIT_L(0); PG8_MMA(0, 0, At, B0); PG8_BAR; PG8_SCHED;
;     ...
;         for (int a = 0; a < 2; ++a)
; #pragma unroll
;             for (int b = 0; b < 2; ++b)
; #pragma unroll
;                 for (int m = 0; m < 4; ++m)
; #pragma unroll
;                     for (int n = 0; n < 2; ++n) acc[a][b][m][n] = (f32x4){0.f, 0.f, 0.f, 0.f}; }
.LBB0_103:
	s_ashr_i32 s43, s42, 31
	v_mov_b64_e32 v[2:3], 0xb16
	s_lshl_b64 s[22:23], s[42:43], 19
	v_cmp_lt_i64_e32 vcc, s[44:45], v[2:3]
	s_add_u32 s44, s36, s22
	s_addc_u32 s45, s37, s23
	s_and_b64 s[22:23], vcc, exec
	s_cselect_b32 s43, s45, s63
	s_cselect_b32 s61, s44, s62
	s_ashr_i32 s41, s40, 31
	s_lshl_b64 s[22:23], s[40:41], 19
	s_add_u32 s58, s29, s22
	s_addc_u32 s59, s9, s23
	s_and_b64 s[22:23], vcc, exec
	s_cselect_b32 s41, s59, s65
	s_cselect_b32 s69, s58, s64
	s_add_u32 s62, s62, 0x40080
	s_addc_u32 s63, s63, 0
	s_add_u32 s70, s64, 0x100
	v_mov_b32_e32 v2, 0
	s_addc_u32 s71, s65, 0
	s_mov_b32 s74, -2
	v_add_u32_e32 v151, 0x10000, v147
	ds_read_b128 v[156:159], v151
	ds_read_b128 v[160:163], v151 offset:1024
	ds_read_b128 v[164:167], v151 offset:2048
	ds_read_b128 v[168:171], v151 offset:3072
	v_mov_b32_e32 v3, v2
	v_mov_b32_e32 v4, v2
	v_mov_b32_e32 v5, v2
	v_mov_b32_e32 v10, v2
	v_mov_b32_e32 v11, v2
	v_mov_b32_e32 v12, v2
	v_mov_b32_e32 v13, v2
	v_mov_b32_e32 v18, v2
	v_mov_b32_e32 v19, v2
	v_mov_b32_e32 v20, v2
	v_mov_b32_e32 v21, v2
	v_mov_b32_e32 v26, v2
	v_mov_b32_e32 v27, v2
	v_mov_b32_e32 v28, v2
	v_mov_b32_e32 v29, v2
	v_mov_b32_e32 v34, v2
	v_mov_b32_e32 v35, v2
	v_mov_b32_e32 v36, v2
	v_mov_b32_e32 v37, v2
	v_mov_b32_e32 v42, v2
	v_mov_b32_e32 v43, v2
	v_mov_b32_e32 v44, v2
	v_mov_b32_e32 v45, v2
	v_mov_b32_e32 v50, v2
	v_mov_b32_e32 v51, v2
	v_mov_b32_e32 v52, v2
	v_mov_b32_e32 v53, v2
	v_mov_b32_e32 v58, v2
	v_mov_b32_e32 v59, v2
	v_mov_b32_e32 v60, v2
	v_mov_b32_e32 v61, v2
	v_mov_b32_e32 v6, v2
	v_mov_b32_e32 v7, v2
	v_mov_b32_e32 v8, v2
	v_mov_b32_e32 v9, v2
	v_mov_b32_e32 v14, v2
	v_mov_b32_e32 v15, v2
	v_mov_b32_e32 v16, v2
	v_mov_b32_e32 v17, v2
	v_mov_b32_e32 v22, v2
	v_mov_b32_e32 v23, v2
	v_mov_b32_e32 v24, v2
	v_mov_b32_e32 v25, v2
	v_mov_b32_e32 v30, v2
	v_mov_b32_e32 v31, v2
	v_mov_b32_e32 v32, v2
	v_mov_b32_e32 v33, v2
	v_mov_b32_e32 v38, v2
	v_mov_b32_e32 v39, v2
	v_mov_b32_e32 v40, v2
	v_mov_b32_e32 v41, v2
	v_mov_b32_e32 v46, v2
	v_mov_b32_e32 v47, v2
	v_mov_b32_e32 v48, v2
	v_mov_b32_e32 v49, v2
	v_mov_b32_e32 v54, v2
	v_mov_b32_e32 v55, v2
	v_mov_b32_e32 v56, v2
	v_mov_b32_e32 v57, v2
	v_mov_b32_e32 v62, v2
	v_mov_b32_e32 v63, v2
	v_mov_b32_e32 v64, v2
	v_mov_b32_e32 v65, v2
	v_mov_b32_e32 v66, v2
	v_mov_b32_e32 v67, v2
	v_mov_b32_e32 v68, v2
	v_mov_b32_e32 v69, v2
	v_mov_b32_e32 v74, v2
	v_mov_b32_e32 v75, v2
	v_mov_b32_e32 v76, v2
	v_mov_b32_e32 v77, v2
	v_mov_b32_e32 v82, v2
	v_mov_b32_e32 v83, v2
	v_mov_b32_e32 v84, v2
	v_mov_b32_e32 v85, v2
	v_mov_b32_e32 v90, v2
	v_mov_b32_e32 v91, v2
	v_mov_b32_e32 v92, v2
	v_mov_b32_e32 v93, v2
	v_mov_b32_e32 v98, v2
	v_mov_b32_e32 v99, v2
	v_mov_b32_e32 v100, v2
	v_mov_b32_e32 v101, v2
	v_mov_b32_e32 v106, v2
	v_mov_b32_e32 v107, v2
	v_mov_b32_e32 v108, v2
	v_mov_b32_e32 v109, v2
	v_mov_b32_e32 v114, v2
	v_mov_b32_e32 v115, v2
	v_mov_b32_e32 v116, v2
	v_mov_b32_e32 v117, v2
	v_mov_b32_e32 v122, v2
	v_mov_b32_e32 v123, v2
	v_mov_b32_e32 v124, v2
	v_mov_b32_e32 v125, v2
	v_mov_b32_e32 v70, v2
	v_mov_b32_e32 v71, v2
	v_mov_b32_e32 v72, v2
	v_mov_b32_e32 v73, v2
	v_mov_b32_e32 v78, v2
	v_mov_b32_e32 v79, v2
	v_mov_b32_e32 v80, v2
	v_mov_b32_e32 v81, v2
	v_mov_b32_e32 v86, v2
	v_mov_b32_e32 v87, v2
	v_mov_b32_e32 v88, v2
	v_mov_b32_e32 v89, v2
	v_mov_b32_e32 v94, v2
	v_mov_b32_e32 v95, v2
	v_mov_b32_e32 v96, v2
	v_mov_b32_e32 v97, v2
	v_mov_b32_e32 v102, v2
	v_mov_b32_e32 v103, v2
	v_mov_b32_e32 v104, v2
	v_mov_b32_e32 v105, v2
	v_mov_b32_e32 v110, v2
	v_mov_b32_e32 v111, v2
	v_mov_b32_e32 v112, v2
	v_mov_b32_e32 v113, v2
	v_mov_b32_e32 v118, v2
	v_mov_b32_e32 v119, v2
	v_mov_b32_e32 v120, v2
	v_mov_b32_e32 v121, v2
	v_mov_b32_e32 v126, v2
	v_mov_b32_e32 v127, v2
	v_mov_b32_e32 v128, v2
	v_mov_b32_e32 v129, v2
.LBB0_104:
	s_add_u32 s22, s62, 0xfffc0080
	s_addc_u32 s23, s63, -1
	s_add_i32 s75, 0, 0x10000
	s_cmp_eq_u32 s74, 12
	s_cselect_b32 s67, s43, s23
	s_cselect_b32 s66, s61, s22
	s_cselect_b32 s65, s41, s71
	s_cselect_b32 s64, s69, s70
	s_add_i32 m0, s50, 0xc000
	ds_read_b128 v[172:175], v149
	ds_read_b128 v[176:179], v149 offset:1024
	ds_read_b128 v[180:183], v149 offset:2048
	ds_read_b128 v[184:187], v149 offset:3072
	ds_read_b128 v[188:191], v149 offset:4096
	ds_read_b128 v[192:195], v149 offset:5120
	ds_read_b128 v[202:205], v149 offset:6144
	ds_read_b128 v[206:209], v149 offset:7168
	global_load_lds_dwordx4 v138, s[62:63]
	s_add_i32 m0, s50, 0xe000
	s_nop 0
	global_load_lds_dwordx4 v140, s[62:63]
	s_waitcnt lgkmcnt(8)
	s_barrier
	s_waitcnt lgkmcnt(0)
	s_setprio 1
	v_mfma_f32_16x16x32_bf16 v[126:129], v[156:159], v[172:175], v[126:129]
	v_mfma_f32_16x16x32_bf16 v[118:121], v[164:167], v[172:175], v[118:121]
	v_mfma_f32_16x16x32_bf16 v[110:113], v[156:159], v[180:183], v[110:113]
	v_mfma_f32_16x16x32_bf16 v[102:105], v[164:167], v[180:183], v[102:105]
	v_mfma_f32_16x16x32_bf16 v[94:97], v[156:159], v[188:191], v[94:97]
	v_mfma_f32_16x16x32_bf16 v[86:89], v[164:167], v[188:191], v[86:89]
	v_mfma_f32_16x16x32_bf16 v[78:81], v[156:159], v[202:205], v[78:81]
	v_mfma_f32_16x16x32_bf16 v[70:73], v[164:167], v[202:205], v[70:73]
	v_mfma_f32_16x16x32_bf16 v[126:129], v[160:163], v[176:179], v[126:129]
	v_mfma_f32_16x16x32_bf16 v[118:121], v[168:171], v[176:179], v[118:121]
	v_mfma_f32_16x16x32_bf16 v[110:113], v[160:163], v[184:187], v[110:113]
	v_mfma_f32_16x16x32_bf16 v[102:105], v[168:171], v[184:187], v[102:105]
	v_mfma_f32_16x16x32_bf16 v[94:97], v[160:163], v[192:195], v[94:97]
	v_mfma_f32_16x16x32_bf16 v[86:89], v[168:171], v[192:195], v[86:89]
	v_mfma_f32_16x16x32_bf16 v[78:81], v[160:163], v[206:209], v[78:81]
	v_mfma_f32_16x16x32_bf16 v[70:73], v[168:171], v[206:209], v[70:73]
	s_setprio 0
	s_barrier
; #define PG8_STAGE(bufoff, gbase, voff) do { _Pragma("unroll") for (int _i = 0; _i < 2; ++_i) \
;         __builtin_amdgcn_global_load_lds((const unsigned*)((const char*)(gbase) + (voff)[_i]), (LAS unsigned*)(lds + (bufoff) + ldsw + _i * 8192), 16, 0, 0); } while (0)
; #define PG8_LDA(dst, b, h) do { _Pragma("unroll") for (int m = 0; m < 4; ++m) _Pragma("unroll") for (int k = 0; k < 2; ++k) dst[m][k] = *(const LAS bf16x8*)(lds + PG8_SA(b, h) + aoff + m * 2048 + k * 1024); } while (0)
; #define PG8_LDB(dst, b, h) do { _Pragma("unroll") for (int n = 0; n < 2; ++n) _Pragma("unroll") for (int k = 0; k < 2; ++k) dst[n][k] = *(const LAS bf16x8*)(lds + PG8_SB(b, h) + boff + n * 2048 + k * 1024); } while (0)
; #define PG8_MMA(ai, bj, At, Bt) do { __builtin_amdgcn_s_setprio(1); _Pragma("unroll") for (int m = 0; m < 4; ++m) _Pragma("unroll") for (int n = 0; n < 2; ++n) _Pragma("unroll") for (int k = 0; k < 2; ++k) \
;         acc[ai][bj][m][n] = __builtin_amdgcn_mfma_f32_16x16x32_bf16(Bt[n][k], At[m][k], acc[ai][bj][m][n], 0, 0, 0); __builtin_amdgcn_s_setprio(0); } while (0)
; #define PG8_WAIT_V(n) asm volatile("s_waitcnt vmcnt(" #n ")" ::: "memory")
; #define PG8_WAIT_L(n) asm volatile("s_waitcnt lgkmcnt(" #n ")" ::: "memory")
; #define PG8_BAR __builtin_amdgcn_s_barrier()
; #define PG8_SCHED __builtin_amdgcn_sched_barrier(0)
; template <class Epi>
; __device__ __forceinline__ void gemm_phase(LAS unsigned char* lds, const Gemm g, const StaticOrder& S, const Epi& E) {
;     ...
;             PG8_LDB(B1, 0, 1); PG8_STAGE(PG8_SB(0, 0), b2, voffB);
;             PG8_BAR; PG8_WAIT_L(0); PG8_MMA(0, 1, At, B1); PG8_BAR;
;             PG8_LDA(At, 0, 1); PG8_STAGE(PG8_SA(0, 0), a2, voffA);
;             PG8_BAR; PG8_WAIT_L(0); PG8_MMA(1, 0, At, B0); PG8_BAR; PG8_SCHED;
;             PG8_STAGE(PG8_SB(0, 1), b2 + hB, voffB);
;             PG8_WAIT_V(6); PG8_BAR; PG8_MMA(1, 1, At, B1); PG8_BAR;
;             PG8_LDB(B0, 1, 0); PG8_SCHED; PG8_LDA(At, 1, 0); PG8_STAGE(PG8_SA(0, 1), a2 + hA, voffA);
;             PG8_WAIT_L(8); PG8_BAR; PG8_WAIT_L(0); PG8_MMA(0, 0, At, B0); PG8_BAR; PG8_SCHED;
	s_add_i32 s76, 0, 0x14000
	s_add_i32 s22, s75, s48
	s_mov_b32 m0, s22
	ds_read_b128 v[210:213], v151 offset:16384
	ds_read_b128 v[214:217], v151 offset:17408
	ds_read_b128 v[218:221], v151 offset:18432
	ds_read_b128 v[222:225], v151 offset:19456
	global_load_lds_dwordx4 v0, s[64:65]
	s_add_i32 m0, s22, 0x2000
	s_nop 0
	global_load_lds_dwordx4 v134, s[64:65]
	s_barrier
	s_waitcnt lgkmcnt(0)
	s_setprio 1
	v_mfma_f32_16x16x32_bf16 v[122:125], v[210:213], v[172:175], v[122:125]
	v_mfma_f32_16x16x32_bf16 v[114:117], v[218:221], v[172:175], v[114:117]
	v_mfma_f32_16x16x32_bf16 v[106:109], v[210:213], v[180:183], v[106:109]
	v_mfma_f32_16x16x32_bf16 v[98:101], v[218:221], v[180:183], v[98:101]
	v_mfma_f32_16x16x32_bf16 v[90:93], v[210:213], v[188:191], v[90:93]
	v_mfma_f32_16x16x32_bf16 v[82:85], v[218:221], v[188:191], v[82:85]
	v_mfma_f32_16x16x32_bf16 v[74:77], v[210:213], v[202:205], v[74:77]
	v_mfma_f32_16x16x32_bf16 v[66:69], v[218:221], v[202:205], v[66:69]
	v_mfma_f32_16x16x32_bf16 v[122:125], v[214:217], v[176:179], v[122:125]
	v_mfma_f32_16x16x32_bf16 v[114:117], v[222:225], v[176:179], v[114:117]
	v_mfma_f32_16x16x32_bf16 v[106:109], v[214:217], v[184:187], v[106:109]
	v_mfma_f32_16x16x32_bf16 v[98:101], v[222:225], v[184:187], v[98:101]
	v_mfma_f32_16x16x32_bf16 v[90:93], v[214:217], v[192:195], v[90:93]
	v_mfma_f32_16x16x32_bf16 v[82:85], v[222:225], v[192:195], v[82:85]
	v_mfma_f32_16x16x32_bf16 v[74:77], v[214:217], v[206:209], v[74:77]
	v_mfma_f32_16x16x32_bf16 v[66:69], v[222:225], v[206:209], v[66:69]
	s_setprio 0
	s_mov_b32 m0, s50
	s_barrier
	ds_read_b128 v[172:175], v149 offset:16384
	ds_read_b128 v[176:179], v149 offset:17408
	ds_read_b128 v[180:183], v149 offset:18432
	ds_read_b128 v[184:187], v149 offset:19456
	ds_read_b128 v[188:191], v149 offset:20480
	ds_read_b128 v[192:195], v149 offset:21504
	ds_read_b128 v[202:205], v149 offset:22528
	ds_read_b128 v[206:209], v149 offset:23552
	global_load_lds_dwordx4 v130, s[66:67]
	s_mov_b32 m0, s51
	s_nop 0
	global_load_lds_dwordx4 v132, s[66:67]
	s_waitcnt vmcnt(8)
	s_barrier
	s_waitcnt lgkmcnt(0)
	s_setprio 1
	v_mfma_f32_16x16x32_bf16 v[62:65], v[156:159], v[172:175], v[62:65]
	v_mfma_f32_16x16x32_bf16 v[54:57], v[164:167], v[172:175], v[54:57]
	v_mfma_f32_16x16x32_bf16 v[46:49], v[156:159], v[180:183], v[46:49]
	v_mfma_f32_16x16x32_bf16 v[38:41], v[164:167], v[180:183], v[38:41]
	v_mfma_f32_16x16x32_bf16 v[30:33], v[156:159], v[188:191], v[30:33]
	v_mfma_f32_16x16x32_bf16 v[22:25], v[164:167], v[188:191], v[22:25]
	v_mfma_f32_16x16x32_bf16 v[14:17], v[156:159], v[202:205], v[14:17]
	v_mfma_f32_16x16x32_bf16 v[6:9], v[164:167], v[202:205], v[6:9]
	v_mfma_f32_16x16x32_bf16 v[62:65], v[160:163], v[176:179], v[62:65]
	v_mfma_f32_16x16x32_bf16 v[54:57], v[168:171], v[176:179], v[54:57]
	v_mfma_f32_16x16x32_bf16 v[46:49], v[160:163], v[184:187], v[46:49]
	v_mfma_f32_16x16x32_bf16 v[38:41], v[168:171], v[184:187], v[38:41]
	v_mfma_f32_16x16x32_bf16 v[30:33], v[160:163], v[192:195], v[30:33]
	v_mfma_f32_16x16x32_bf16 v[22:25], v[168:171], v[192:195], v[22:25]
	v_mfma_f32_16x16x32_bf16 v[14:17], v[160:163], v[206:209], v[14:17]
	v_mfma_f32_16x16x32_bf16 v[6:9], v[168:171], v[206:209], v[6:9]
	s_setprio 0
	s_barrier
	s_add_u32 s22, s64, 0x40000
	s_addc_u32 s23, s65, 0
	s_add_i32 s75, s76, s48
	s_mov_b32 m0, s75
	s_nop 0
	global_load_lds_dwordx4 v0, s[22:23]
	s_add_i32 m0, s75, 0x2000
	s_nop 0
	global_load_lds_dwordx4 v134, s[22:23]
	s_waitcnt vmcnt(6)
	s_barrier
	s_setprio 1
	v_mfma_f32_16x16x32_bf16 v[58:61], v[210:213], v[172:175], v[58:61]
	ds_read_b128 v[156:159], v151 offset:32768
	v_mfma_f32_16x16x32_bf16 v[50:53], v[218:221], v[172:175], v[50:53]
	ds_read_b128 v[160:163], v151 offset:33792
	v_mfma_f32_16x16x32_bf16 v[42:45], v[210:213], v[180:183], v[42:45]
	ds_read_b128 v[164:167], v151 offset:34816
	v_mfma_f32_16x16x32_bf16 v[34:37], v[218:221], v[180:183], v[34:37]
	ds_read_b128 v[168:171], v151 offset:35840
	v_mfma_f32_16x16x32_bf16 v[26:29], v[210:213], v[188:191], v[26:29]
	v_mfma_f32_16x16x32_bf16 v[18:21], v[218:221], v[188:191], v[18:21]
	v_mfma_f32_16x16x32_bf16 v[10:13], v[210:213], v[202:205], v[10:13]
	v_mfma_f32_16x16x32_bf16 v[2:5], v[218:221], v[202:205], v[2:5]
	v_mfma_f32_16x16x32_bf16 v[58:61], v[214:217], v[176:179], v[58:61]
	v_mfma_f32_16x16x32_bf16 v[50:53], v[222:225], v[176:179], v[50:53]
	v_mfma_f32_16x16x32_bf16 v[42:45], v[214:217], v[184:187], v[42:45]
	v_mfma_f32_16x16x32_bf16 v[34:37], v[222:225], v[184:187], v[34:37]
	v_mfma_f32_16x16x32_bf16 v[26:29], v[214:217], v[192:195], v[26:29]
	v_mfma_f32_16x16x32_bf16 v[18:21], v[222:225], v[192:195], v[18:21]
	v_mfma_f32_16x16x32_bf16 v[10:13], v[214:217], v[206:209], v[10:13]
	v_mfma_f32_16x16x32_bf16 v[2:5], v[222:225], v[206:209], v[2:5]
	s_setprio 0
	s_add_i32 s75, 0, 0x18000
	s_barrier
	s_add_u32 s22, s66, 0x40000
	s_addc_u32 s23, s67, 0
	s_mov_b32 m0, s53
	ds_read_b128 v[172:175], v149 offset:32768
	ds_read_b128 v[176:179], v149 offset:33792
	ds_read_b128 v[180:183], v149 offset:34816
	ds_read_b128 v[184:187], v149 offset:35840
	ds_read_b128 v[188:191], v149 offset:36864
	ds_read_b128 v[192:195], v149 offset:37888
	ds_read_b128 v[202:205], v149 offset:38912
	ds_read_b128 v[206:209], v149 offset:39936
	global_load_lds_dwordx4 v130, s[22:23]
	s_mov_b32 m0, s54
	s_nop 0
	global_load_lds_dwordx4 v132, s[22:23]
	s_waitcnt lgkmcnt(8)
	s_barrier
; #define PG8_STAGE(bufoff, gbase, voff) do { _Pragma("unroll") for (int _i = 0; _i < 2; ++_i) \
;         __builtin_amdgcn_global_load_lds((const unsigned*)((const char*)(gbase) + (voff)[_i]), (LAS unsigned*)(lds + (bufoff) + ldsw + _i * 8192), 16, 0, 0); } while (0)
; #define PG8_LDA(dst, b, h) do { _Pragma("unroll") for (int m = 0; m < 4; ++m) _Pragma("unroll") for (int k = 0; k < 2; ++k) dst[m][k] = *(const LAS bf16x8*)(lds + PG8_SA(b, h) + aoff + m * 2048 + k * 1024); } while (0)
; #define PG8_LDB(dst, b, h) do { _Pragma("unroll") for (int n = 0; n < 2; ++n) _Pragma("unroll") for (int k = 0; k < 2; ++k) dst[n][k] = *(const LAS bf16x8*)(lds + PG8_SB(b, h) + boff + n * 2048 + k * 1024); } while (0)
; #define PG8_MMA(ai, bj, At, Bt) do { __builtin_amdgcn_s_setprio(1); _Pragma("unroll") for (int m = 0; m < 4; ++m) _Pragma("unroll") for (int n = 0; n < 2; ++n) _Pragma("unroll") for (int k = 0; k < 2; ++k) \
;         acc[ai][bj][m][n] = __builtin_amdgcn_mfma_f32_16x16x32_bf16(Bt[n][k], At[m][k], acc[ai][bj][m][n], 0, 0, 0); __builtin_amdgcn_s_setprio(0); } while (0)
; #define PG8_WAIT_V(n) asm volatile("s_waitcnt vmcnt(" #n ")" ::: "memory")
; #define PG8_WAIT_L(n) asm volatile("s_waitcnt lgkmcnt(" #n ")" ::: "memory")
; #define PG8_BAR __builtin_amdgcn_s_barrier()
; #define PG8_SCHED __builtin_amdgcn_sched_barrier(0)
; template <class Epi>
; __device__ __forceinline__ void gemm_phase(LAS unsigned char* lds, const Gemm g, const StaticOrder& S, const Epi& E) {
;     ...
;             PG8_LDB(B0, 1, 0); PG8_SCHED; PG8_LDA(At, 1, 0); PG8_STAGE(PG8_SA(0, 1), a2 + hA, voffA);
;             PG8_WAIT_L(8); PG8_BAR; PG8_WAIT_L(0); PG8_MMA(0, 0, At, B0); PG8_BAR; PG8_SCHED;
;             PG8_LDB(B1, 1, 1); PG8_STAGE(PG8_SB(1, 0), b3, voffB);
;             PG8_BAR; PG8_WAIT_L(0); PG8_MMA(0, 1, At, B1); PG8_BAR;
;             PG8_LDA(At, 1, 1); PG8_STAGE(PG8_SA(1, 0), a3, voffA);
;             PG8_BAR; PG8_WAIT_L(0); PG8_MMA(1, 0, At, B0); PG8_BAR; PG8_SCHED;
;             PG8_STAGE(PG8_SB(1, 1), b3 + hB, voffB);
;             PG8_WAIT_V(6); PG8_BAR; PG8_MMA(1, 1, At, B1); PG8_BAR;
	s_waitcnt lgkmcnt(0)
	s_setprio 1
	v_mfma_f32_16x16x32_bf16 v[126:129], v[156:159], v[172:175], v[126:129]
	v_mfma_f32_16x16x32_bf16 v[118:121], v[164:167], v[172:175], v[118:121]
	v_mfma_f32_16x16x32_bf16 v[110:113], v[156:159], v[180:183], v[110:113]
	v_mfma_f32_16x16x32_bf16 v[102:105], v[164:167], v[180:183], v[102:105]
	v_mfma_f32_16x16x32_bf16 v[94:97], v[156:159], v[188:191], v[94:97]
	v_mfma_f32_16x16x32_bf16 v[86:89], v[164:167], v[188:191], v[86:89]
	v_mfma_f32_16x16x32_bf16 v[78:81], v[156:159], v[202:205], v[78:81]
	v_mfma_f32_16x16x32_bf16 v[70:73], v[164:167], v[202:205], v[70:73]
	v_mfma_f32_16x16x32_bf16 v[126:129], v[160:163], v[176:179], v[126:129]
	v_mfma_f32_16x16x32_bf16 v[118:121], v[168:171], v[176:179], v[118:121]
	v_mfma_f32_16x16x32_bf16 v[110:113], v[160:163], v[184:187], v[110:113]
	v_mfma_f32_16x16x32_bf16 v[102:105], v[168:171], v[184:187], v[102:105]
	v_mfma_f32_16x16x32_bf16 v[94:97], v[160:163], v[192:195], v[94:97]
	v_mfma_f32_16x16x32_bf16 v[86:89], v[168:171], v[192:195], v[86:89]
	v_mfma_f32_16x16x32_bf16 v[78:81], v[160:163], v[206:209], v[78:81]
	v_mfma_f32_16x16x32_bf16 v[70:73], v[168:171], v[206:209], v[70:73]
	s_setprio 0
	s_barrier
	s_add_i32 s22, s75, s48
	s_add_u32 s100, s64, 0x80
	s_addc_u32 s101, s65, 0
	s_mov_b32 m0, s22
	ds_read_b128 v[210:213], v151 offset:49152
	ds_read_b128 v[214:217], v151 offset:50176
	ds_read_b128 v[218:221], v151 offset:51200
	ds_read_b128 v[222:225], v151 offset:52224
	global_load_lds_dwordx4 v0, s[100:101]
	s_add_i32 m0, s22, 0x2000
	s_nop 0
	global_load_lds_dwordx4 v134, s[100:101]
	s_barrier
	s_waitcnt lgkmcnt(0)
	s_setprio 1
	v_mfma_f32_16x16x32_bf16 v[122:125], v[210:213], v[172:175], v[122:125]
	v_mfma_f32_16x16x32_bf16 v[114:117], v[218:221], v[172:175], v[114:117]
	v_mfma_f32_16x16x32_bf16 v[106:109], v[210:213], v[180:183], v[106:109]
	v_mfma_f32_16x16x32_bf16 v[98:101], v[218:221], v[180:183], v[98:101]
	v_mfma_f32_16x16x32_bf16 v[90:93], v[210:213], v[188:191], v[90:93]
	v_mfma_f32_16x16x32_bf16 v[82:85], v[218:221], v[188:191], v[82:85]
	v_mfma_f32_16x16x32_bf16 v[74:77], v[210:213], v[202:205], v[74:77]
	v_mfma_f32_16x16x32_bf16 v[66:69], v[218:221], v[202:205], v[66:69]
	v_mfma_f32_16x16x32_bf16 v[122:125], v[214:217], v[176:179], v[122:125]
	v_mfma_f32_16x16x32_bf16 v[114:117], v[222:225], v[176:179], v[114:117]
	v_mfma_f32_16x16x32_bf16 v[106:109], v[214:217], v[184:187], v[106:109]
	v_mfma_f32_16x16x32_bf16 v[98:101], v[222:225], v[184:187], v[98:101]
	v_mfma_f32_16x16x32_bf16 v[90:93], v[214:217], v[192:195], v[90:93]
	v_mfma_f32_16x16x32_bf16 v[82:85], v[222:225], v[192:195], v[82:85]
	v_mfma_f32_16x16x32_bf16 v[74:77], v[214:217], v[206:209], v[74:77]
	v_mfma_f32_16x16x32_bf16 v[66:69], v[222:225], v[206:209], v[66:69]
	s_setprio 0
	s_mov_b32 m0, s56
	s_add_u32 s100, s66, 0x80
	s_addc_u32 s101, s67, 0
	s_barrier
	ds_read_b128 v[172:175], v149 offset:49152
	ds_read_b128 v[176:179], v149 offset:50176
	ds_read_b128 v[180:183], v149 offset:51200
	ds_read_b128 v[184:187], v149 offset:52224
	ds_read_b128 v[188:191], v149 offset:53248
	ds_read_b128 v[192:195], v149 offset:54272
	ds_read_b128 v[202:205], v149 offset:55296
	ds_read_b128 v[206:209], v149 offset:56320
	global_load_lds_dwordx4 v130, s[100:101]
	s_mov_b32 m0, s57
	s_nop 0
	global_load_lds_dwordx4 v132, s[100:101]
	s_waitcnt vmcnt(8)
	s_barrier
	s_waitcnt lgkmcnt(0)
	s_setprio 1
	v_mfma_f32_16x16x32_bf16 v[62:65], v[156:159], v[172:175], v[62:65]
	v_mfma_f32_16x16x32_bf16 v[54:57], v[164:167], v[172:175], v[54:57]
	v_mfma_f32_16x16x32_bf16 v[46:49], v[156:159], v[180:183], v[46:49]
	v_mfma_f32_16x16x32_bf16 v[38:41], v[164:167], v[180:183], v[38:41]
	v_mfma_f32_16x16x32_bf16 v[30:33], v[156:159], v[188:191], v[30:33]
	v_mfma_f32_16x16x32_bf16 v[22:25], v[164:167], v[188:191], v[22:25]
	v_mfma_f32_16x16x32_bf16 v[14:17], v[156:159], v[202:205], v[14:17]
	v_mfma_f32_16x16x32_bf16 v[6:9], v[164:167], v[202:205], v[6:9]
	v_mfma_f32_16x16x32_bf16 v[62:65], v[160:163], v[176:179], v[62:65]
	v_mfma_f32_16x16x32_bf16 v[54:57], v[168:171], v[176:179], v[54:57]
	v_mfma_f32_16x16x32_bf16 v[46:49], v[160:163], v[184:187], v[46:49]
	v_mfma_f32_16x16x32_bf16 v[38:41], v[168:171], v[184:187], v[38:41]
	v_mfma_f32_16x16x32_bf16 v[30:33], v[160:163], v[192:195], v[30:33]
	v_mfma_f32_16x16x32_bf16 v[22:25], v[168:171], v[192:195], v[22:25]
	v_mfma_f32_16x16x32_bf16 v[14:17], v[160:163], v[206:209], v[14:17]
	v_mfma_f32_16x16x32_bf16 v[6:9], v[168:171], v[206:209], v[6:9]
	s_setprio 0
	s_barrier
	s_add_u32 s22, s64, 0x40080
	s_addc_u32 s23, s65, 0
	s_add_i32 s64, s48, 0x1c000
	s_mov_b32 m0, s64
	s_nop 0
	global_load_lds_dwordx4 v0, s[22:23]
	s_add_i32 m0, s64, 0x2000
	s_nop 0
	global_load_lds_dwordx4 v134, s[22:23]
	s_waitcnt vmcnt(6)
	s_barrier
	s_setprio 1
	v_mfma_f32_16x16x32_bf16 v[58:61], v[210:213], v[172:175], v[58:61]
	ds_read_b128 v[156:159], v151
	v_mfma_f32_16x16x32_bf16 v[50:53], v[218:221], v[172:175], v[50:53]
	ds_read_b128 v[160:163], v151 offset:1024
	v_mfma_f32_16x16x32_bf16 v[42:45], v[210:213], v[180:183], v[42:45]
	ds_read_b128 v[164:167], v151 offset:2048
	v_mfma_f32_16x16x32_bf16 v[34:37], v[218:221], v[180:183], v[34:37]
	ds_read_b128 v[168:171], v151 offset:3072
	v_mfma_f32_16x16x32_bf16 v[26:29], v[210:213], v[188:191], v[26:29]
	v_mfma_f32_16x16x32_bf16 v[18:21], v[218:221], v[188:191], v[18:21]
	v_mfma_f32_16x16x32_bf16 v[10:13], v[210:213], v[202:205], v[10:13]
	v_mfma_f32_16x16x32_bf16 v[2:5], v[218:221], v[202:205], v[2:5]
	v_mfma_f32_16x16x32_bf16 v[58:61], v[214:217], v[176:179], v[58:61]
	v_mfma_f32_16x16x32_bf16 v[50:53], v[222:225], v[176:179], v[50:53]
	v_mfma_f32_16x16x32_bf16 v[42:45], v[214:217], v[184:187], v[42:45]
	v_mfma_f32_16x16x32_bf16 v[34:37], v[222:225], v[184:187], v[34:37]
	v_mfma_f32_16x16x32_bf16 v[26:29], v[214:217], v[192:195], v[26:29]
	v_mfma_f32_16x16x32_bf16 v[18:21], v[222:225], v[192:195], v[18:21]
	v_mfma_f32_16x16x32_bf16 v[10:13], v[214:217], v[206:209], v[10:13]
	v_mfma_f32_16x16x32_bf16 v[2:5], v[222:225], v[206:209], v[2:5]
	s_setprio 0
	s_add_i32 s74, s74, 2
	s_add_u32 s62, s62, 0x100
	s_addc_u32 s63, s63, 0
	s_add_u32 s70, s70, 0x100
	s_addc_u32 s71, s71, 0
	s_cmp_gt_u32 s74, 13
	s_barrier
; __device__ __forceinline__ float siluf_(float x) { return x * sigmoidf_(x); }
; __device__ __forceinline__ u32x4 pack8(const f32x4 a, const f32x4 b) { u32x4 w; w.x = cvt_pk_bf16(a[0], a[1]); w.y = cvt_pk_bf16(a[2], a[3]); w.z = cvt_pk_bf16(b[0], b[1]); w.w = cvt_pk_bf16(b[2], b[3]); return w; }
;     __device__ __forceinline__ void operator()(const Acc& acc, const Unit& u, int wr, int wc, int fr, int fq, const RsPre& pr) const {
;         asm volatile("" : "+v"(fr), "+v"(fq));
;         const int row0 = u.pm * 256 + wr * 64 + fr, col0 = u.pn * 128 + wc * 32 + 8 * fq;
;         const float (&rs)[2][4] = pr.rs;
; #pragma unroll
;         for (int ai = 0; ai < 2; ++ai)
; #pragma unroll
;             for (int m = 0; m < 4; ++m) { f32x4 o[2];
; #pragma unroll
;                 for (int n = 0; n < 2; ++n) { const f32x4 a1 = acc[ai][0][m][n] * rs[ai][m], a3 = acc[ai][1][m][n] * rs[ai][m];
;                     o[n] = (f32x4){siluf_(a1[0]) * a3[0], siluf_(a1[1]) * a3[1], siluf_(a1[2]) * a3[2], siluf_(a1[3]) * a3[3]}; }
;                 *(u32x4*)(ff + (size_t)(row0 + ai * 128 + m * 16) * DFF + col0) = pack8(o[0], o[1]); }
	s_cbranch_scc0 .LBB0_104
	s_waitcnt lgkmcnt(0)
	v_mov_b32_e32 v151, v137
	v_mov_b32_e32 v153, v143
	s_lshl_b32 s22, s60, 8
	s_add_i32 s22, s22, s49
	v_add_u32_e32 v151, s22, v151
	s_lshl_b32 s22, s33, 7
	s_or_b32 s22, s22, s55
	s_waitcnt vmcnt(0)
	v_pk_mul_f32 v[126:127], v[154:155], v[126:127] op_sel_hi:[0,1]
	v_lshl_add_u32 v156, v153, 3, s22
	v_mul_f32_e32 v153, 0xbfb8aa3b, v126
	v_exp_f32_e32 v153, v153
	v_pk_mul_f32 v[128:129], v[154:155], v[128:129] op_sel_hi:[0,1]
	v_pk_mul_f32 v[122:123], v[154:155], v[122:123] op_sel_hi:[0,1]
	v_pk_mul_f32 v[124:125], v[154:155], v[124:125] op_sel_hi:[0,1]
	v_add_f32_e32 v153, 1.0, v153
	v_rcp_f32_e32 v158, v153
	v_mul_f32_e32 v153, 0xbfb8aa3b, v127
	v_exp_f32_e32 v153, v153
	v_pk_mul_f32 v[118:119], v[154:155], v[118:119] op_sel_hi:[0,1]
	v_pk_mul_f32 v[120:121], v[154:155], v[120:121] op_sel_hi:[0,1]
	v_pk_mul_f32 v[114:115], v[154:155], v[114:115] op_sel_hi:[0,1]
	v_add_f32_e32 v153, 1.0, v153
	v_rcp_f32_e32 v159, v153
	v_pk_mul_f32 v[116:117], v[154:155], v[116:117] op_sel_hi:[0,1]
	s_movk_i32 s0, 0x1600
	v_pk_mul_f32 v[126:127], v[126:127], v[158:159]
	v_pk_mul_f32 v[110:111], v[152:153], v[110:111] op_sel_hi:[0,1]
	v_pk_mul_f32 v[122:123], v[126:127], v[122:123]
	v_mul_f32_e32 v126, 0xbfb8aa3b, v128
	v_mul_f32_e32 v127, 0xbfb8aa3b, v129
	v_exp_f32_e32 v126, v126
	v_exp_f32_e32 v127, v127
	v_pk_mul_f32 v[112:113], v[152:153], v[112:113] op_sel_hi:[0,1]
	v_pk_mul_f32 v[106:107], v[152:153], v[106:107] op_sel_hi:[0,1]
	v_add_f32_e32 v126, 1.0, v126
	v_add_f32_e32 v127, 1.0, v127
	v_rcp_f32_e32 v126, v126
	v_rcp_f32_e32 v127, v127
	v_pk_mul_f32 v[108:109], v[152:153], v[108:109] op_sel_hi:[0,1]
	v_pk_mul_f32 v[102:103], v[152:153], v[102:103] op_sel_hi:[0,1]
	v_pk_mul_f32 v[104:105], v[152:153], v[104:105] op_sel_hi:[0,1]
	v_pk_mul_f32 v[126:127], v[128:129], v[126:127]
	v_pk_mul_f32 v[98:99], v[152:153], v[98:99] op_sel_hi:[0,1]
	v_pk_mul_f32 v[124:125], v[126:127], v[124:125]
	v_mul_f32_e32 v126, 0xbfb8aa3b, v118
	v_mul_f32_e32 v127, 0xbfb8aa3b, v119
	v_exp_f32_e32 v126, v126
	v_exp_f32_e32 v127, v127
	v_pk_mul_f32 v[100:101], v[152:153], v[100:101] op_sel_hi:[0,1]
	v_pk_mul_f32 v[94:95], v[150:151], v[94:95] op_sel_hi:[0,1]
	v_add_f32_e32 v126, 1.0, v126
	v_add_f32_e32 v127, 1.0, v127
	v_rcp_f32_e32 v126, v126
	v_rcp_f32_e32 v127, v127
	v_pk_mul_f32 v[96:97], v[150:151], v[96:97] op_sel_hi:[0,1]
	v_pk_mul_f32 v[90:91], v[150:151], v[90:91] op_sel_hi:[0,1]
	v_pk_mul_f32 v[92:93], v[150:151], v[92:93] op_sel_hi:[0,1]
	v_pk_mul_f32 v[118:119], v[118:119], v[126:127]
	v_pk_mul_f32 v[86:87], v[150:151], v[86:87] op_sel_hi:[0,1]
	v_pk_mul_f32 v[114:115], v[118:119], v[114:115]
	v_mul_f32_e32 v118, 0xbfb8aa3b, v120
	v_mul_f32_e32 v119, 0xbfb8aa3b, v121
	v_exp_f32_e32 v118, v118
	v_exp_f32_e32 v119, v119
	v_pk_mul_f32 v[88:89], v[150:151], v[88:89] op_sel_hi:[0,1]
	v_pk_mul_f32 v[82:83], v[150:151], v[82:83] op_sel_hi:[0,1]
	v_add_f32_e32 v118, 1.0, v118
	v_add_f32_e32 v119, 1.0, v119
	v_rcp_f32_e32 v118, v118
	v_rcp_f32_e32 v119, v119
	v_pk_mul_f32 v[84:85], v[150:151], v[84:85] op_sel_hi:[0,1]
	v_pk_mul_f32 v[78:79], v[148:149], v[78:79] op_sel_hi:[0,1]
	v_pk_mul_f32 v[80:81], v[148:149], v[80:81] op_sel_hi:[0,1]
	v_pk_mul_f32 v[118:119], v[120:121], v[118:119]
	v_cvt_pk_bf16_f32 v120, v114, v115
	v_pk_mul_f32 v[116:117], v[118:119], v[116:117]
	v_cvt_pk_bf16_f32 v118, v122, v123
	v_cvt_pk_bf16_f32 v121, v116, v117
	v_lshlrev_b32_e32 v116, 1, v156
	v_mad_u32_u24 v114, v151, s0, v116
	v_cvt_pk_bf16_f32 v119, v124, v125
	global_store_dwordx4 v114, v[118:121], s[20:21]
	v_pk_mul_f32 v[74:75], v[148:149], v[74:75] op_sel_hi:[0,1]
	v_pk_mul_f32 v[76:77], v[148:149], v[76:77] op_sel_hi:[0,1]
	v_mul_f32_e32 v118, 0xbfb8aa3b, v110
	v_mul_f32_e32 v119, 0xbfb8aa3b, v111
	v_exp_f32_e32 v118, v118
	v_exp_f32_e32 v119, v119
	v_pk_mul_f32 v[70:71], v[148:149], v[70:71] op_sel_hi:[0,1]
	v_pk_mul_f32 v[72:73], v[148:149], v[72:73] op_sel_hi:[0,1]
	v_add_f32_e32 v118, 1.0, v118
	v_add_f32_e32 v119, 1.0, v119
	v_rcp_f32_e32 v118, v118
	v_rcp_f32_e32 v119, v119
	v_pk_mul_f32 v[66:67], v[148:149], v[66:67] op_sel_hi:[0,1]
	v_pk_mul_f32 v[68:69], v[148:149], v[68:69] op_sel_hi:[0,1]
	v_pk_mul_f32 v[62:63], v[146:147], v[62:63] op_sel_hi:[0,1]
	v_pk_mul_f32 v[110:111], v[110:111], v[118:119]
	v_pk_mul_f32 v[64:65], v[146:147], v[64:65] op_sel_hi:[0,1]
	v_pk_mul_f32 v[106:107], v[110:111], v[106:107]
	v_mul_f32_e32 v110, 0xbfb8aa3b, v112
	v_mul_f32_e32 v111, 0xbfb8aa3b, v113
	v_exp_f32_e32 v110, v110
	v_exp_f32_e32 v111, v111
	v_pk_mul_f32 v[58:59], v[146:147], v[58:59] op_sel_hi:[0,1]
	v_pk_mul_f32 v[60:61], v[146:147], v[60:61] op_sel_hi:[0,1]
	v_add_f32_e32 v110, 1.0, v110
	v_add_f32_e32 v111, 1.0, v111
	v_rcp_f32_e32 v110, v110
	v_rcp_f32_e32 v111, v111
	v_pk_mul_f32 v[54:55], v[146:147], v[54:55] op_sel_hi:[0,1]
	v_pk_mul_f32 v[56:57], v[146:147], v[56:57] op_sel_hi:[0,1]
	v_pk_mul_f32 v[50:51], v[146:147], v[50:51] op_sel_hi:[0,1]
	v_pk_mul_f32 v[110:111], v[112:113], v[110:111]
	v_pk_mul_f32 v[52:53], v[146:147], v[52:53] op_sel_hi:[0,1]
	v_pk_mul_f32 v[108:109], v[110:111], v[108:109]
	v_mul_f32_e32 v110, 0xbfb8aa3b, v102
	v_mul_f32_e32 v111, 0xbfb8aa3b, v103
	v_exp_f32_e32 v110, v110
	v_exp_f32_e32 v111, v111
	v_pk_mul_f32 v[46:47], v[144:145], v[46:47] op_sel_hi:[0,1]
	v_pk_mul_f32 v[48:49], v[144:145], v[48:49] op_sel_hi:[0,1]
	v_add_f32_e32 v110, 1.0, v110
	v_add_f32_e32 v111, 1.0, v111
	v_rcp_f32_e32 v110, v110
	v_rcp_f32_e32 v111, v111
	v_pk_mul_f32 v[42:43], v[144:145], v[42:43] op_sel_hi:[0,1]
	v_pk_mul_f32 v[44:45], v[144:145], v[44:45] op_sel_hi:[0,1]
	v_pk_mul_f32 v[38:39], v[144:145], v[38:39] op_sel_hi:[0,1]
; __device__ __forceinline__ float siluf_(float x) { return x * sigmoidf_(x); }
; __device__ __forceinline__ u32x4 pack8(const f32x4 a, const f32x4 b) { u32x4 w; w.x = cvt_pk_bf16(a[0], a[1]); w.y = cvt_pk_bf16(a[2], a[3]); w.z = cvt_pk_bf16(b[0], b[1]); w.w = cvt_pk_bf16(b[2], b[3]); return w; }
;     __device__ __forceinline__ void operator()(const Acc& acc, const Unit& u, int wr, int wc, int fr, int fq, const RsPre& pr) const {
;     ...
;         for (int ai = 0; ai < 2; ++ai)
; #pragma unroll
;             for (int m = 0; m < 4; ++m) { f32x4 o[2];
; #pragma unroll
;                 for (int n = 0; n < 2; ++n) { const f32x4 a1 = acc[ai][0][m][n] * rs[ai][m], a3 = acc[ai][1][m][n] * rs[ai][m];
;                     o[n] = (f32x4){siluf_(a1[0]) * a3[0], siluf_(a1[1]) * a3[1], siluf_(a1[2]) * a3[2], siluf_(a1[3]) * a3[3]}; }
;                 *(u32x4*)(ff + (size_t)(row0 + ai * 128 + m * 16) * DFF + col0) = pack8(o[0], o[1]); }
	v_pk_mul_f32 v[102:103], v[102:103], v[110:111]
	v_pk_mul_f32 v[40:41], v[144:145], v[40:41] op_sel_hi:[0,1]
	v_pk_mul_f32 v[102:103], v[102:103], v[98:99]
	v_mul_f32_e32 v98, 0xbfb8aa3b, v104
	v_mul_f32_e32 v99, 0xbfb8aa3b, v105
	v_exp_f32_e32 v98, v98
	v_exp_f32_e32 v99, v99
	v_pk_mul_f32 v[34:35], v[144:145], v[34:35] op_sel_hi:[0,1]
	v_pk_mul_f32 v[36:37], v[144:145], v[36:37] op_sel_hi:[0,1]
	v_add_f32_e32 v98, 1.0, v98
	v_add_f32_e32 v99, 1.0, v99
	v_rcp_f32_e32 v98, v98
	v_rcp_f32_e32 v99, v99
	v_pk_mul_f32 v[30:31], v[142:143], v[30:31] op_sel_hi:[0,1]
	v_pk_mul_f32 v[32:33], v[142:143], v[32:33] op_sel_hi:[0,1]
	v_pk_mul_f32 v[26:27], v[142:143], v[26:27] op_sel_hi:[0,1]
	v_pk_mul_f32 v[98:99], v[104:105], v[98:99]
	v_pk_mul_f32 v[28:29], v[142:143], v[28:29] op_sel_hi:[0,1]
	v_pk_mul_f32 v[104:105], v[98:99], v[100:101]
	v_cvt_pk_bf16_f32 v100, v102, v103
	v_cvt_pk_bf16_f32 v98, v106, v107
	v_cvt_pk_bf16_f32 v99, v108, v109
	v_cvt_pk_bf16_f32 v101, v104, v105
	v_add_u32_e32 v102, 0x16000, v114
	global_store_dwordx4 v102, v[98:101], s[20:21]
	v_pk_mul_f32 v[22:23], v[142:143], v[22:23] op_sel_hi:[0,1]
	v_pk_mul_f32 v[24:25], v[142:143], v[24:25] op_sel_hi:[0,1]
	v_mul_f32_e32 v98, 0xbfb8aa3b, v94
	v_mul_f32_e32 v99, 0xbfb8aa3b, v95
	v_exp_f32_e32 v98, v98
	v_exp_f32_e32 v99, v99
	v_pk_mul_f32 v[18:19], v[142:143], v[18:19] op_sel_hi:[0,1]
	v_pk_mul_f32 v[20:21], v[142:143], v[20:21] op_sel_hi:[0,1]
	v_add_f32_e32 v98, 1.0, v98
	v_add_f32_e32 v99, 1.0, v99
	v_rcp_f32_e32 v98, v98
	v_rcp_f32_e32 v99, v99
	v_pk_mul_f32 v[14:15], v[136:137], v[14:15] op_sel_hi:[0,1]
	v_pk_mul_f32 v[16:17], v[136:137], v[16:17] op_sel_hi:[0,1]
	v_pk_mul_f32 v[10:11], v[136:137], v[10:11] op_sel_hi:[0,1]
	v_pk_mul_f32 v[94:95], v[94:95], v[98:99]
	v_pk_mul_f32 v[12:13], v[136:137], v[12:13] op_sel_hi:[0,1]
	v_pk_mul_f32 v[90:91], v[94:95], v[90:91]
	v_mul_f32_e32 v94, 0xbfb8aa3b, v96
	v_mul_f32_e32 v95, 0xbfb8aa3b, v97
	v_exp_f32_e32 v94, v94
	v_exp_f32_e32 v95, v95
	v_pk_mul_f32 v[6:7], v[136:137], v[6:7] op_sel_hi:[0,1]
	v_pk_mul_f32 v[8:9], v[136:137], v[8:9] op_sel_hi:[0,1]
	v_add_f32_e32 v94, 1.0, v94
	v_add_f32_e32 v95, 1.0, v95
	v_rcp_f32_e32 v94, v94
	v_rcp_f32_e32 v95, v95
	v_pk_mul_f32 v[2:3], v[136:137], v[2:3] op_sel_hi:[0,1]
	v_pk_mul_f32 v[4:5], v[136:137], v[4:5] op_sel_hi:[0,1]
	s_mov_b64 s[60:61], -1
	v_pk_mul_f32 v[94:95], v[96:97], v[94:95]
	s_and_b64 vcc, vcc, exec
	v_pk_mul_f32 v[92:93], v[94:95], v[92:93]
	v_mul_f32_e32 v94, 0xbfb8aa3b, v86
	v_mul_f32_e32 v95, 0xbfb8aa3b, v87
	v_exp_f32_e32 v94, v94
	v_exp_f32_e32 v95, v95
	v_add_f32_e32 v94, 1.0, v94
	v_add_f32_e32 v95, 1.0, v95
	v_rcp_f32_e32 v94, v94
	v_rcp_f32_e32 v95, v95
	s_nop 0
	v_pk_mul_f32 v[86:87], v[86:87], v[94:95]
	s_nop 0
	v_pk_mul_f32 v[86:87], v[86:87], v[82:83]
	v_mul_f32_e32 v82, 0xbfb8aa3b, v88
	v_mul_f32_e32 v83, 0xbfb8aa3b, v89
	v_exp_f32_e32 v82, v82
	v_exp_f32_e32 v83, v83
	v_add_f32_e32 v82, 1.0, v82
	v_add_f32_e32 v83, 1.0, v83
	v_rcp_f32_e32 v82, v82
	v_rcp_f32_e32 v83, v83
	s_nop 0
	v_pk_mul_f32 v[82:83], v[88:89], v[82:83]
	s_nop 0
	v_pk_mul_f32 v[88:89], v[82:83], v[84:85]
	v_cvt_pk_bf16_f32 v84, v86, v87
	v_cvt_pk_bf16_f32 v82, v90, v91
	v_cvt_pk_bf16_f32 v83, v92, v93
	v_cvt_pk_bf16_f32 v85, v88, v89
	v_add_u32_e32 v86, 0x2c000, v114
	global_store_dwordx4 v86, v[82:85], s[20:21]
	s_nop 1
	v_mul_f32_e32 v82, 0xbfb8aa3b, v78
	v_mul_f32_e32 v83, 0xbfb8aa3b, v79
	v_exp_f32_e32 v82, v82
	v_exp_f32_e32 v83, v83
	v_add_f32_e32 v82, 1.0, v82
	v_add_f32_e32 v83, 1.0, v83
	v_rcp_f32_e32 v82, v82
	v_rcp_f32_e32 v83, v83
	s_nop 0
	v_pk_mul_f32 v[78:79], v[78:79], v[82:83]
	s_nop 0
	v_pk_mul_f32 v[74:75], v[78:79], v[74:75]
	v_mul_f32_e32 v78, 0xbfb8aa3b, v80
	v_mul_f32_e32 v79, 0xbfb8aa3b, v81
	v_exp_f32_e32 v78, v78
	v_exp_f32_e32 v79, v79
	v_add_f32_e32 v78, 1.0, v78
	v_add_f32_e32 v79, 1.0, v79
	v_rcp_f32_e32 v78, v78
	v_rcp_f32_e32 v79, v79
	s_nop 0
	v_pk_mul_f32 v[78:79], v[80:81], v[78:79]
	s_nop 0
	v_pk_mul_f32 v[76:77], v[78:79], v[76:77]
	v_mul_f32_e32 v78, 0xbfb8aa3b, v70
	v_mul_f32_e32 v79, 0xbfb8aa3b, v71
	v_exp_f32_e32 v78, v78
	v_exp_f32_e32 v79, v79
	v_add_f32_e32 v78, 1.0, v78
	v_add_f32_e32 v79, 1.0, v79
	v_rcp_f32_e32 v78, v78
	v_rcp_f32_e32 v79, v79
	s_nop 0
	v_pk_mul_f32 v[70:71], v[70:71], v[78:79]
	s_nop 0
	v_pk_mul_f32 v[70:71], v[70:71], v[66:67]
	v_mul_f32_e32 v66, 0xbfb8aa3b, v72
	v_mul_f32_e32 v67, 0xbfb8aa3b, v73
	v_exp_f32_e32 v66, v66
	v_exp_f32_e32 v67, v67
	v_add_f32_e32 v66, 1.0, v66
	v_add_f32_e32 v67, 1.0, v67
	v_rcp_f32_e32 v66, v66
	v_rcp_f32_e32 v67, v67
	s_nop 0
	v_pk_mul_f32 v[66:67], v[72:73], v[66:67]
	s_nop 0
	v_pk_mul_f32 v[72:73], v[66:67], v[68:69]
	v_cvt_pk_bf16_f32 v68, v70, v71
	v_cvt_pk_bf16_f32 v66, v74, v75
	v_cvt_pk_bf16_f32 v67, v76, v77
	v_cvt_pk_bf16_f32 v69, v72, v73
	v_add_u32_e32 v70, 0x42000, v114
	global_store_dwordx4 v70, v[66:69], s[20:21]
	s_nop 1
	v_mul_f32_e32 v66, 0xbfb8aa3b, v62
	v_mul_f32_e32 v67, 0xbfb8aa3b, v63
	v_exp_f32_e32 v66, v66
	v_exp_f32_e32 v67, v67
	v_add_f32_e32 v66, 1.0, v66
	v_add_f32_e32 v67, 1.0, v67
	v_rcp_f32_e32 v66, v66
	v_rcp_f32_e32 v67, v67
	s_nop 0
	v_pk_mul_f32 v[62:63], v[62:63], v[66:67]
	s_nop 0
	v_pk_mul_f32 v[58:59], v[62:63], v[58:59]
	v_mul_f32_e32 v62, 0xbfb8aa3b, v64
	v_mul_f32_e32 v63, 0xbfb8aa3b, v65
	v_exp_f32_e32 v62, v62
	v_exp_f32_e32 v63, v63
	v_add_f32_e32 v62, 1.0, v62
	v_add_f32_e32 v63, 1.0, v63
	v_rcp_f32_e32 v62, v62
	v_rcp_f32_e32 v63, v63
	s_nop 0
	v_pk_mul_f32 v[62:63], v[64:65], v[62:63]
	s_nop 0
	v_pk_mul_f32 v[60:61], v[62:63], v[60:61]
	v_mul_f32_e32 v62, 0xbfb8aa3b, v54
	v_mul_f32_e32 v63, 0xbfb8aa3b, v55
	v_exp_f32_e32 v62, v62
; __device__ __forceinline__ float siluf_(float x) { return x * sigmoidf_(x); }
; __device__ __forceinline__ u32x4 pack8(const f32x4 a, const f32x4 b) { u32x4 w; w.x = cvt_pk_bf16(a[0], a[1]); w.y = cvt_pk_bf16(a[2], a[3]); w.z = cvt_pk_bf16(b[0], b[1]); w.w = cvt_pk_bf16(b[2], b[3]); return w; }
;     __device__ __forceinline__ void pre(RsPre& r, const Unit& u, int wr, int fr) const {
; #pragma unroll
;         for (int ai = 0; ai < 2; ++ai)
; #pragma unroll
;             for (int m = 0; m < 4; ++m) r.rs[ai][m] = rsv[u.pm * 256 + wr * 64 + fr + ai * 128 + m * 16]; }
;     __device__ __forceinline__ void operator()(const Acc& acc, const Unit& u, int wr, int wc, int fr, int fq, const RsPre& pr) const {
;     ...
;         for (int ai = 0; ai < 2; ++ai)
; #pragma unroll
;             for (int m = 0; m < 4; ++m) { f32x4 o[2];
; #pragma unroll
;                 for (int n = 0; n < 2; ++n) { const f32x4 a1 = acc[ai][0][m][n] * rs[ai][m], a3 = acc[ai][1][m][n] * rs[ai][m];
;                     o[n] = (f32x4){siluf_(a1[0]) * a3[0], siluf_(a1[1]) * a3[1], siluf_(a1[2]) * a3[2], siluf_(a1[3]) * a3[3]}; }
;                 *(u32x4*)(ff + (size_t)(row0 + ai * 128 + m * 16) * DFF + col0) = pack8(o[0], o[1]); }
	v_exp_f32_e32 v63, v63
	v_add_f32_e32 v62, 1.0, v62
	v_add_f32_e32 v63, 1.0, v63
	v_rcp_f32_e32 v62, v62
	v_rcp_f32_e32 v63, v63
	s_nop 0
	v_pk_mul_f32 v[54:55], v[54:55], v[62:63]
	s_nop 0
	v_pk_mul_f32 v[54:55], v[54:55], v[50:51]
	v_mul_f32_e32 v50, 0xbfb8aa3b, v56
	v_mul_f32_e32 v51, 0xbfb8aa3b, v57
	v_exp_f32_e32 v50, v50
	v_exp_f32_e32 v51, v51
	v_add_f32_e32 v50, 1.0, v50
	v_add_f32_e32 v51, 1.0, v51
	v_rcp_f32_e32 v50, v50
	v_rcp_f32_e32 v51, v51
	s_nop 0
	v_pk_mul_f32 v[50:51], v[56:57], v[50:51]
	s_nop 0
	v_pk_mul_f32 v[56:57], v[50:51], v[52:53]
	v_cvt_pk_bf16_f32 v52, v54, v55
	v_cvt_pk_bf16_f32 v50, v58, v59
	v_cvt_pk_bf16_f32 v51, v60, v61
	v_cvt_pk_bf16_f32 v53, v56, v57
	v_add_u32_e32 v54, 0xb0000, v114
	global_store_dwordx4 v54, v[50:53], s[20:21]
	s_nop 1
	v_mul_f32_e32 v50, 0xbfb8aa3b, v46
	v_mul_f32_e32 v51, 0xbfb8aa3b, v47
	v_exp_f32_e32 v50, v50
	v_exp_f32_e32 v51, v51
	v_add_f32_e32 v50, 1.0, v50
	v_add_f32_e32 v51, 1.0, v51
	v_rcp_f32_e32 v50, v50
	v_rcp_f32_e32 v51, v51
	s_nop 0
	v_pk_mul_f32 v[46:47], v[46:47], v[50:51]
	s_nop 0
	v_pk_mul_f32 v[42:43], v[46:47], v[42:43]
	v_mul_f32_e32 v46, 0xbfb8aa3b, v48
	v_mul_f32_e32 v47, 0xbfb8aa3b, v49
	v_exp_f32_e32 v46, v46
	v_exp_f32_e32 v47, v47
	v_add_f32_e32 v46, 1.0, v46
	v_add_f32_e32 v47, 1.0, v47
	v_rcp_f32_e32 v46, v46
	v_rcp_f32_e32 v47, v47
	s_nop 0
	v_pk_mul_f32 v[46:47], v[48:49], v[46:47]
	s_nop 0
	v_pk_mul_f32 v[44:45], v[46:47], v[44:45]
	v_mul_f32_e32 v46, 0xbfb8aa3b, v38
	v_mul_f32_e32 v47, 0xbfb8aa3b, v39
	v_exp_f32_e32 v46, v46
	v_exp_f32_e32 v47, v47
	v_add_f32_e32 v46, 1.0, v46
	v_add_f32_e32 v47, 1.0, v47
	v_rcp_f32_e32 v46, v46
	v_rcp_f32_e32 v47, v47
	s_nop 0
	v_pk_mul_f32 v[38:39], v[38:39], v[46:47]
	s_nop 0
	v_pk_mul_f32 v[38:39], v[38:39], v[34:35]
	v_mul_f32_e32 v34, 0xbfb8aa3b, v40
	v_mul_f32_e32 v35, 0xbfb8aa3b, v41
	v_exp_f32_e32 v34, v34
	v_exp_f32_e32 v35, v35
	v_add_f32_e32 v34, 1.0, v34
	v_add_f32_e32 v35, 1.0, v35
	v_rcp_f32_e32 v34, v34
	v_rcp_f32_e32 v35, v35
	s_nop 0
	v_pk_mul_f32 v[34:35], v[40:41], v[34:35]
	s_nop 0
	v_pk_mul_f32 v[40:41], v[34:35], v[36:37]
	v_cvt_pk_bf16_f32 v36, v38, v39
	v_cvt_pk_bf16_f32 v34, v42, v43
	v_cvt_pk_bf16_f32 v35, v44, v45
	v_cvt_pk_bf16_f32 v37, v40, v41
	v_add_u32_e32 v38, 0xc6000, v114
	global_store_dwordx4 v38, v[34:37], s[20:21]
	s_nop 1
	v_mul_f32_e32 v34, 0xbfb8aa3b, v30
	v_mul_f32_e32 v35, 0xbfb8aa3b, v31
	v_exp_f32_e32 v34, v34
	v_exp_f32_e32 v35, v35
	v_add_f32_e32 v34, 1.0, v34
	v_add_f32_e32 v35, 1.0, v35
	v_rcp_f32_e32 v34, v34
	v_rcp_f32_e32 v35, v35
	s_nop 0
	v_pk_mul_f32 v[30:31], v[30:31], v[34:35]
	s_nop 0
	v_pk_mul_f32 v[26:27], v[30:31], v[26:27]
	v_mul_f32_e32 v30, 0xbfb8aa3b, v32
	v_mul_f32_e32 v31, 0xbfb8aa3b, v33
	v_exp_f32_e32 v30, v30
	v_exp_f32_e32 v31, v31
	v_add_f32_e32 v30, 1.0, v30
	v_add_f32_e32 v31, 1.0, v31
	v_rcp_f32_e32 v30, v30
	v_rcp_f32_e32 v31, v31
	s_nop 0
	v_pk_mul_f32 v[30:31], v[32:33], v[30:31]
	s_nop 0
	v_pk_mul_f32 v[28:29], v[30:31], v[28:29]
	v_mul_f32_e32 v30, 0xbfb8aa3b, v22
	v_mul_f32_e32 v31, 0xbfb8aa3b, v23
	v_exp_f32_e32 v30, v30
	v_exp_f32_e32 v31, v31
	v_add_f32_e32 v30, 1.0, v30
	v_add_f32_e32 v31, 1.0, v31
	v_rcp_f32_e32 v30, v30
	v_rcp_f32_e32 v31, v31
	s_nop 0
	v_pk_mul_f32 v[22:23], v[22:23], v[30:31]
	s_nop 0
	v_pk_mul_f32 v[22:23], v[22:23], v[18:19]
	v_mul_f32_e32 v18, 0xbfb8aa3b, v24
	v_mul_f32_e32 v19, 0xbfb8aa3b, v25
	v_exp_f32_e32 v18, v18
	v_exp_f32_e32 v19, v19
	v_add_f32_e32 v18, 1.0, v18
	v_add_f32_e32 v19, 1.0, v19
	v_rcp_f32_e32 v18, v18
	v_rcp_f32_e32 v19, v19
	s_nop 0
	v_pk_mul_f32 v[18:19], v[24:25], v[18:19]
	s_nop 0
	v_pk_mul_f32 v[24:25], v[18:19], v[20:21]
	v_cvt_pk_bf16_f32 v20, v22, v23
	v_cvt_pk_bf16_f32 v18, v26, v27
	v_cvt_pk_bf16_f32 v19, v28, v29
	v_cvt_pk_bf16_f32 v21, v24, v25
	v_add_u32_e32 v22, 0xdc000, v114
	global_store_dwordx4 v22, v[18:21], s[20:21]
	s_nop 1
	v_mul_f32_e32 v18, 0xbfb8aa3b, v14
	v_mul_f32_e32 v19, 0xbfb8aa3b, v15
	v_exp_f32_e32 v18, v18
	v_exp_f32_e32 v19, v19
	v_add_f32_e32 v18, 1.0, v18
	v_add_f32_e32 v19, 1.0, v19
	v_rcp_f32_e32 v18, v18
	v_rcp_f32_e32 v19, v19
	s_nop 0
	v_pk_mul_f32 v[14:15], v[14:15], v[18:19]
	s_nop 0
	v_pk_mul_f32 v[10:11], v[14:15], v[10:11]
	v_mul_f32_e32 v14, 0xbfb8aa3b, v16
	v_mul_f32_e32 v15, 0xbfb8aa3b, v17
	v_exp_f32_e32 v14, v14
	v_exp_f32_e32 v15, v15
	v_add_f32_e32 v14, 1.0, v14
	v_add_f32_e32 v15, 1.0, v15
	v_rcp_f32_e32 v14, v14
	v_rcp_f32_e32 v15, v15
	s_nop 0
	v_pk_mul_f32 v[14:15], v[16:17], v[14:15]
	s_nop 0
	v_pk_mul_f32 v[12:13], v[14:15], v[12:13]
	v_mul_f32_e32 v14, 0xbfb8aa3b, v6
	v_mul_f32_e32 v15, 0xbfb8aa3b, v7
	v_exp_f32_e32 v14, v14
	v_exp_f32_e32 v15, v15
	v_add_f32_e32 v14, 1.0, v14
	v_add_f32_e32 v15, 1.0, v15
	v_rcp_f32_e32 v14, v14
	v_rcp_f32_e32 v15, v15
	s_nop 0
	v_pk_mul_f32 v[6:7], v[6:7], v[14:15]
	s_nop 0
	v_pk_mul_f32 v[6:7], v[6:7], v[2:3]
	v_mul_f32_e32 v2, 0xbfb8aa3b, v8
	v_mul_f32_e32 v3, 0xbfb8aa3b, v9
	v_exp_f32_e32 v2, v2
	v_exp_f32_e32 v3, v3
	v_add_f32_e32 v2, 1.0, v2
	v_add_f32_e32 v3, 1.0, v3
	v_rcp_f32_e32 v2, v2
	v_rcp_f32_e32 v3, v3
	s_nop 0
	v_pk_mul_f32 v[2:3], v[8:9], v[2:3]
	s_nop 0
	v_pk_mul_f32 v[8:9], v[2:3], v[4:5]
	v_cvt_pk_bf16_f32 v4, v6, v7
	v_cvt_pk_bf16_f32 v2, v10, v11
	v_cvt_pk_bf16_f32 v3, v12, v13
	v_cvt_pk_bf16_f32 v5, v8, v9
	v_add_u32_e32 v6, 0xf2000, v114
	global_store_dwordx4 v6, v[2:5], s[20:21]
	s_cbranch_vccz .LBB0_96
	s_nop 0
	v_lshl_add_u32 v2, s42, 8, v145
	v_ashrrev_i32_e32 v3, 31, v2
	v_lshl_add_u64 v[2:3], v[2:3], 2, s[4:5]
	global_load_dword v154, v[2:3], off
	global_load_dword v152, v[2:3], off offset:64
	global_load_dword v150, v[2:3], off offset:128
	global_load_dword v148, v[2:3], off offset:192
	global_load_dword v146, v[2:3], off offset:512
	global_load_dword v144, v[2:3], off offset:576
	global_load_dword v142, v[2:3], off offset:640
	global_load_dword v136, v[2:3], off offset:704
	s_mov_b64 s[60:61], 0
	s_branch .LBB0_96

; #define PG8_STAGE(bufoff, gbase, voff) do { _Pragma("unroll") for (int _i = 0; _i < 2; ++_i) \
;         __builtin_amdgcn_global_load_lds((const unsigned*)((const char*)(gbase) + (voff)[_i]), (LAS unsigned*)(lds + (bufoff) + ldsw + _i * 8192), 16, 0, 0); } while (0)
; #define PG8_LDA(dst, b, h) do { _Pragma("unroll") for (int m = 0; m < 4; ++m) _Pragma("unroll") for (int k = 0; k < 2; ++k) dst[m][k] = *(const LAS bf16x8*)(lds + PG8_SA(b, h) + aoff + m * 2048 + k * 1024); } while (0)
; #define PG8_LDB(dst, b, h) do { _Pragma("unroll") for (int n = 0; n < 2; ++n) _Pragma("unroll") for (int k = 0; k < 2; ++k) dst[n][k] = *(const LAS bf16x8*)(lds + PG8_SB(b, h) + boff + n * 2048 + k * 1024); } while (0)
; #define PG8_WAIT_L(n) asm volatile("s_waitcnt lgkmcnt(" #n ")" ::: "memory")
; #define PG8_BAR __builtin_amdgcn_s_barrier()
; #define PG8_SCHED __builtin_amdgcn_sched_barrier(0)
; template <class Epi>
; __device__ __forceinline__ void gemm_phase(LAS unsigned char* lds, const Gemm g, const StaticOrder& S, const Epi& E) {
;     ...
;         const bool has_next = S.next(ui + 1, nxt);
;         const char* nA = has_next ? (const char*)(nxt.alt ? g.A2 : g.A) + (size_t)nxt.pm * tA + (size_t)nxt.k0 * 2 : cA; const char* nB = has_next ? (const char*)(nxt.alt ? g.Bt2 : g.Bt) + (size_t)nxt.pn * tB + (size_t)nxt.k0 * 2 : cB;
;         const int nt = cur.nt;
;         for (int t = 0; t < nt; t += 2) {
;             const bool last = (t == nt - 2);
;             const char* a1 = cA + (size_t)(t + 1) * kstep;
;             const char* a2 = last ? nA : cA + (size_t)(t + 2) * kstep; const char* b2 = last ? nB : cB + (size_t)(t + 2) * kstep;
;             const char* a3 = a2 + kstep; const char* b3 = b2 + kstep;
;             PG8_LDB(B0, 0, 0); PG8_SCHED; PG8_LDA(At, 0, 0); PG8_STAGE(PG8_SA(1, 1), a1 + hA, voffA);
;             PG8_WAIT_L(8); PG8_BAR; PG8_WAIT_L(0); PG8_MMA(0, 0, At, B0); PG8_BAR; PG8_SCHED;
;     ...
;         for (int a = 0; a < 2; ++a)
; #pragma unroll
;             for (int b = 0; b < 2; ++b)
; #pragma unroll
;                 for (int m = 0; m < 4; ++m)
; #pragma unroll
;                     for (int n = 0; n < 2; ++n) acc[a][b][m][n] = (f32x4){0.f, 0.f, 0.f, 0.f}; }
;         cur = nxt; cA = nA; cB = nB; ++ui;
.LBB0_622:
	v_mov_b64_e32 v[2:3], 0x891
	s_ashr_i32 s23, s22, 31
	v_cmp_lt_i64_e32 vcc, s[40:41], v[2:3]
	s_lshl_b64 s[40:41], s[22:23], 19
	s_add_u32 s40, s36, s40
	s_addc_u32 s41, s37, s41
	s_and_b64 s[42:43], vcc, exec
	s_cselect_b32 s23, s41, s47
	s_cselect_b32 s62, s40, s46
	s_ashr_i32 s15, s14, 31
	s_lshl_b64 s[42:43], s[14:15], 19
	s_add_u32 s42, s8, s42
	s_addc_u32 s43, s9, s43
	s_and_b64 s[50:51], vcc, exec
	s_cselect_b32 s15, s43, s49
	s_cselect_b32 s63, s42, s48
	s_add_u32 s46, s46, 0x40080
	s_addc_u32 s47, s47, 0
	s_add_u32 s64, s48, 0x100
	v_mov_b32_e32 v2, 0
	s_addc_u32 s65, s49, 0
	s_mov_b32 s66, -2
	v_add_u32_e32 v151, 0x10000, v143
	ds_read_b128 v[156:159], v151
	ds_read_b128 v[160:163], v151 offset:1024
	ds_read_b128 v[164:167], v151 offset:2048
	ds_read_b128 v[168:171], v151 offset:3072
	v_mov_b32_e32 v3, v2
	v_mov_b32_e32 v4, v2
	v_mov_b32_e32 v5, v2
	v_mov_b32_e32 v6, v2
	v_mov_b32_e32 v7, v2
	v_mov_b32_e32 v8, v2
	v_mov_b32_e32 v9, v2
	v_mov_b32_e32 v10, v2
	v_mov_b32_e32 v11, v2
	v_mov_b32_e32 v12, v2
	v_mov_b32_e32 v13, v2
	v_mov_b32_e32 v18, v2
	v_mov_b32_e32 v19, v2
	v_mov_b32_e32 v20, v2
	v_mov_b32_e32 v21, v2
	v_mov_b32_e32 v26, v2
	v_mov_b32_e32 v27, v2
	v_mov_b32_e32 v28, v2
	v_mov_b32_e32 v29, v2
	v_mov_b32_e32 v34, v2
	v_mov_b32_e32 v35, v2
	v_mov_b32_e32 v36, v2
	v_mov_b32_e32 v37, v2
	v_mov_b32_e32 v42, v2
	v_mov_b32_e32 v43, v2
	v_mov_b32_e32 v44, v2
	v_mov_b32_e32 v45, v2
	v_mov_b32_e32 v50, v2
	v_mov_b32_e32 v51, v2
	v_mov_b32_e32 v52, v2
	v_mov_b32_e32 v53, v2
	v_mov_b32_e32 v14, v2
	v_mov_b32_e32 v15, v2
	v_mov_b32_e32 v16, v2
	v_mov_b32_e32 v17, v2
	v_mov_b32_e32 v22, v2
	v_mov_b32_e32 v23, v2
	v_mov_b32_e32 v24, v2
	v_mov_b32_e32 v25, v2
	v_mov_b32_e32 v30, v2
	v_mov_b32_e32 v31, v2
	v_mov_b32_e32 v32, v2
	v_mov_b32_e32 v33, v2
	v_mov_b32_e32 v38, v2
	v_mov_b32_e32 v39, v2
	v_mov_b32_e32 v40, v2
	v_mov_b32_e32 v41, v2
	v_mov_b32_e32 v46, v2
	v_mov_b32_e32 v47, v2
	v_mov_b32_e32 v48, v2
	v_mov_b32_e32 v49, v2
	v_mov_b32_e32 v54, v2
	v_mov_b32_e32 v55, v2
	v_mov_b32_e32 v56, v2
	v_mov_b32_e32 v57, v2
	v_mov_b32_e32 v58, v2
	v_mov_b32_e32 v59, v2
	v_mov_b32_e32 v60, v2
	v_mov_b32_e32 v61, v2
	v_mov_b32_e32 v62, v2
	v_mov_b32_e32 v63, v2
	v_mov_b32_e32 v64, v2
	v_mov_b32_e32 v65, v2
	v_mov_b32_e32 v66, v2
	v_mov_b32_e32 v67, v2
	v_mov_b32_e32 v68, v2
	v_mov_b32_e32 v69, v2
	v_mov_b32_e32 v70, v2
	v_mov_b32_e32 v71, v2
	v_mov_b32_e32 v72, v2
	v_mov_b32_e32 v73, v2
	v_mov_b32_e32 v74, v2
	v_mov_b32_e32 v75, v2
	v_mov_b32_e32 v76, v2
	v_mov_b32_e32 v77, v2
	v_mov_b32_e32 v82, v2
	v_mov_b32_e32 v83, v2
	v_mov_b32_e32 v84, v2
	v_mov_b32_e32 v85, v2
	v_mov_b32_e32 v90, v2
	v_mov_b32_e32 v91, v2
	v_mov_b32_e32 v92, v2
	v_mov_b32_e32 v93, v2
	v_mov_b32_e32 v98, v2
	v_mov_b32_e32 v99, v2
	v_mov_b32_e32 v100, v2
	v_mov_b32_e32 v101, v2
	v_mov_b32_e32 v106, v2
	v_mov_b32_e32 v107, v2
	v_mov_b32_e32 v108, v2
	v_mov_b32_e32 v109, v2
	v_mov_b32_e32 v114, v2
	v_mov_b32_e32 v115, v2
	v_mov_b32_e32 v116, v2
	v_mov_b32_e32 v117, v2
	v_mov_b32_e32 v78, v2
	v_mov_b32_e32 v79, v2
	v_mov_b32_e32 v80, v2
	v_mov_b32_e32 v81, v2
	v_mov_b32_e32 v86, v2
	v_mov_b32_e32 v87, v2
	v_mov_b32_e32 v88, v2
	v_mov_b32_e32 v89, v2
	v_mov_b32_e32 v94, v2
	v_mov_b32_e32 v95, v2
	v_mov_b32_e32 v96, v2
	v_mov_b32_e32 v97, v2
	v_mov_b32_e32 v102, v2
	v_mov_b32_e32 v103, v2
	v_mov_b32_e32 v104, v2
	v_mov_b32_e32 v105, v2
	v_mov_b32_e32 v110, v2
	v_mov_b32_e32 v111, v2
	v_mov_b32_e32 v112, v2
	v_mov_b32_e32 v113, v2
	v_mov_b32_e32 v118, v2
	v_mov_b32_e32 v119, v2
	v_mov_b32_e32 v120, v2
	v_mov_b32_e32 v121, v2
	v_mov_b32_e32 v122, v2
	v_mov_b32_e32 v123, v2
	v_mov_b32_e32 v124, v2
	v_mov_b32_e32 v125, v2
	v_mov_b32_e32 v126, v2
	v_mov_b32_e32 v127, v2
	v_mov_b32_e32 v128, v2
	v_mov_b32_e32 v129, v2
.LBB0_623:
	s_add_u32 s48, s46, 0xfffc0080
	s_addc_u32 s49, s47, -1
	s_add_i32 s67, 0, 0x10000
	s_cmp_eq_u32 s66, 12
	s_cselect_b32 s51, s23, s49
	s_cselect_b32 s50, s62, s48
	s_cselect_b32 s49, s15, s65
	s_cselect_b32 s48, s63, s64
	s_add_i32 m0, s53, 0xc000
	ds_read_b128 v[172:175], v149
	ds_read_b128 v[176:179], v149 offset:1024
	ds_read_b128 v[180:183], v149 offset:2048
	ds_read_b128 v[184:187], v149 offset:3072
	ds_read_b128 v[188:191], v149 offset:4096
	ds_read_b128 v[192:195], v149 offset:5120
	ds_read_b128 v[202:205], v149 offset:6144
	ds_read_b128 v[206:209], v149 offset:7168
	global_load_lds_dwordx4 v144, s[46:47]
	s_add_i32 m0, s53, 0xe000
	s_nop 0
	global_load_lds_dwordx4 v146, s[46:47]
	s_waitcnt lgkmcnt(8)
	s_barrier
	s_waitcnt lgkmcnt(0)
	s_setprio 1
	v_mfma_f32_16x16x32_bf16 v[126:129], v[156:159], v[172:175], v[126:129]
	v_mfma_f32_16x16x32_bf16 v[122:125], v[164:167], v[172:175], v[122:125]
	v_mfma_f32_16x16x32_bf16 v[118:121], v[156:159], v[180:183], v[118:121]
	v_mfma_f32_16x16x32_bf16 v[110:113], v[164:167], v[180:183], v[110:113]
	v_mfma_f32_16x16x32_bf16 v[102:105], v[156:159], v[188:191], v[102:105]
	v_mfma_f32_16x16x32_bf16 v[94:97], v[164:167], v[188:191], v[94:97]
	v_mfma_f32_16x16x32_bf16 v[86:89], v[156:159], v[202:205], v[86:89]
	v_mfma_f32_16x16x32_bf16 v[78:81], v[164:167], v[202:205], v[78:81]
	v_mfma_f32_16x16x32_bf16 v[126:129], v[160:163], v[176:179], v[126:129]
	v_mfma_f32_16x16x32_bf16 v[122:125], v[168:171], v[176:179], v[122:125]
	v_mfma_f32_16x16x32_bf16 v[118:121], v[160:163], v[184:187], v[118:121]
	v_mfma_f32_16x16x32_bf16 v[110:113], v[168:171], v[184:187], v[110:113]
	v_mfma_f32_16x16x32_bf16 v[102:105], v[160:163], v[192:195], v[102:105]
	v_mfma_f32_16x16x32_bf16 v[94:97], v[168:171], v[192:195], v[94:97]
	v_mfma_f32_16x16x32_bf16 v[86:89], v[160:163], v[206:209], v[86:89]
	v_mfma_f32_16x16x32_bf16 v[78:81], v[168:171], v[206:209], v[78:81]
	s_setprio 0
	s_barrier
; #define PG8_STAGE(bufoff, gbase, voff) do { _Pragma("unroll") for (int _i = 0; _i < 2; ++_i) \
;         __builtin_amdgcn_global_load_lds((const unsigned*)((const char*)(gbase) + (voff)[_i]), (LAS unsigned*)(lds + (bufoff) + ldsw + _i * 8192), 16, 0, 0); } while (0)
; #define PG8_LDA(dst, b, h) do { _Pragma("unroll") for (int m = 0; m < 4; ++m) _Pragma("unroll") for (int k = 0; k < 2; ++k) dst[m][k] = *(const LAS bf16x8*)(lds + PG8_SA(b, h) + aoff + m * 2048 + k * 1024); } while (0)
; #define PG8_LDB(dst, b, h) do { _Pragma("unroll") for (int n = 0; n < 2; ++n) _Pragma("unroll") for (int k = 0; k < 2; ++k) dst[n][k] = *(const LAS bf16x8*)(lds + PG8_SB(b, h) + boff + n * 2048 + k * 1024); } while (0)
; #define PG8_MMA(ai, bj, At, Bt) do { __builtin_amdgcn_s_setprio(1); _Pragma("unroll") for (int m = 0; m < 4; ++m) _Pragma("unroll") for (int n = 0; n < 2; ++n) _Pragma("unroll") for (int k = 0; k < 2; ++k) \
;         acc[ai][bj][m][n] = __builtin_amdgcn_mfma_f32_16x16x32_bf16(Bt[n][k], At[m][k], acc[ai][bj][m][n], 0, 0, 0); __builtin_amdgcn_s_setprio(0); } while (0)
; #define PG8_WAIT_V(n) asm volatile("s_waitcnt vmcnt(" #n ")" ::: "memory")
; #define PG8_WAIT_L(n) asm volatile("s_waitcnt lgkmcnt(" #n ")" ::: "memory")
; #define PG8_BAR __builtin_amdgcn_s_barrier()
; #define PG8_SCHED __builtin_amdgcn_sched_barrier(0)
; template <class Epi>
; __device__ __forceinline__ void gemm_phase(LAS unsigned char* lds, const Gemm g, const StaticOrder& S, const Epi& E) {
;     ...
;             PG8_LDB(B1, 0, 1); PG8_STAGE(PG8_SB(0, 0), b2, voffB);
;             PG8_BAR; PG8_WAIT_L(0); PG8_MMA(0, 1, At, B1); PG8_BAR;
;             PG8_LDA(At, 0, 1); PG8_STAGE(PG8_SA(0, 0), a2, voffA);
;             PG8_BAR; PG8_WAIT_L(0); PG8_MMA(1, 0, At, B0); PG8_BAR; PG8_SCHED;
;             PG8_STAGE(PG8_SB(0, 1), b2 + hB, voffB);
;             PG8_WAIT_V(6); PG8_BAR; PG8_MMA(1, 1, At, B1); PG8_BAR;
;             PG8_LDB(B0, 1, 0); PG8_SCHED; PG8_LDA(At, 1, 0); PG8_STAGE(PG8_SA(0, 1), a2 + hA, voffA);
	s_add_i32 s70, 0, 0x14000
	s_add_i32 s67, s67, s33
	s_mov_b32 m0, s67
	ds_read_b128 v[210:213], v151 offset:16384
	ds_read_b128 v[214:217], v151 offset:17408
	ds_read_b128 v[218:221], v151 offset:18432
	ds_read_b128 v[222:225], v151 offset:19456
	global_load_lds_dwordx4 v0, s[48:49]
	s_add_i32 m0, s67, 0x2000
	s_nop 0
	global_load_lds_dwordx4 v134, s[48:49]
	s_barrier
	s_waitcnt lgkmcnt(0)
	s_setprio 1
	v_mfma_f32_16x16x32_bf16 v[114:117], v[210:213], v[172:175], v[114:117]
	v_mfma_f32_16x16x32_bf16 v[106:109], v[218:221], v[172:175], v[106:109]
	v_mfma_f32_16x16x32_bf16 v[98:101], v[210:213], v[180:183], v[98:101]
	v_mfma_f32_16x16x32_bf16 v[90:93], v[218:221], v[180:183], v[90:93]
	v_mfma_f32_16x16x32_bf16 v[82:85], v[210:213], v[188:191], v[82:85]
	v_mfma_f32_16x16x32_bf16 v[74:77], v[218:221], v[188:191], v[74:77]
	v_mfma_f32_16x16x32_bf16 v[70:73], v[210:213], v[202:205], v[70:73]
	v_mfma_f32_16x16x32_bf16 v[66:69], v[218:221], v[202:205], v[66:69]
	v_mfma_f32_16x16x32_bf16 v[114:117], v[214:217], v[176:179], v[114:117]
	v_mfma_f32_16x16x32_bf16 v[106:109], v[222:225], v[176:179], v[106:109]
	v_mfma_f32_16x16x32_bf16 v[98:101], v[214:217], v[184:187], v[98:101]
	v_mfma_f32_16x16x32_bf16 v[90:93], v[222:225], v[184:187], v[90:93]
	v_mfma_f32_16x16x32_bf16 v[82:85], v[214:217], v[192:195], v[82:85]
	v_mfma_f32_16x16x32_bf16 v[74:77], v[222:225], v[192:195], v[74:77]
	v_mfma_f32_16x16x32_bf16 v[70:73], v[214:217], v[206:209], v[70:73]
	v_mfma_f32_16x16x32_bf16 v[66:69], v[222:225], v[206:209], v[66:69]
	s_setprio 0
	s_mov_b32 m0, s53
	s_barrier
	ds_read_b128 v[172:175], v149 offset:16384
	ds_read_b128 v[176:179], v149 offset:17408
	ds_read_b128 v[180:183], v149 offset:18432
	ds_read_b128 v[184:187], v149 offset:19456
	ds_read_b128 v[188:191], v149 offset:20480
	ds_read_b128 v[192:195], v149 offset:21504
	ds_read_b128 v[202:205], v149 offset:22528
	ds_read_b128 v[206:209], v149 offset:23552
	global_load_lds_dwordx4 v130, s[50:51]
	s_mov_b32 m0, s54
	s_nop 0
	global_load_lds_dwordx4 v132, s[50:51]
	s_waitcnt vmcnt(8)
	s_barrier
	s_waitcnt lgkmcnt(0)
	s_setprio 1
	v_mfma_f32_16x16x32_bf16 v[62:65], v[156:159], v[172:175], v[62:65]
	v_mfma_f32_16x16x32_bf16 v[58:61], v[164:167], v[172:175], v[58:61]
	v_mfma_f32_16x16x32_bf16 v[54:57], v[156:159], v[180:183], v[54:57]
	v_mfma_f32_16x16x32_bf16 v[46:49], v[164:167], v[180:183], v[46:49]
	v_mfma_f32_16x16x32_bf16 v[38:41], v[156:159], v[188:191], v[38:41]
	v_mfma_f32_16x16x32_bf16 v[30:33], v[164:167], v[188:191], v[30:33]
	v_mfma_f32_16x16x32_bf16 v[22:25], v[156:159], v[202:205], v[22:25]
	v_mfma_f32_16x16x32_bf16 v[14:17], v[164:167], v[202:205], v[14:17]
	v_mfma_f32_16x16x32_bf16 v[62:65], v[160:163], v[176:179], v[62:65]
	v_mfma_f32_16x16x32_bf16 v[58:61], v[168:171], v[176:179], v[58:61]
	v_mfma_f32_16x16x32_bf16 v[54:57], v[160:163], v[184:187], v[54:57]
	v_mfma_f32_16x16x32_bf16 v[46:49], v[168:171], v[184:187], v[46:49]
	v_mfma_f32_16x16x32_bf16 v[38:41], v[160:163], v[192:195], v[38:41]
	v_mfma_f32_16x16x32_bf16 v[30:33], v[168:171], v[192:195], v[30:33]
	v_mfma_f32_16x16x32_bf16 v[22:25], v[160:163], v[206:209], v[22:25]
	v_mfma_f32_16x16x32_bf16 v[14:17], v[168:171], v[206:209], v[14:17]
	s_setprio 0
	s_barrier
	s_add_u32 s68, s48, 0x40000
	s_addc_u32 s69, s49, 0
	s_add_i32 s67, s70, s33
	s_mov_b32 m0, s67
	s_nop 0
	global_load_lds_dwordx4 v0, s[68:69]
	s_add_i32 m0, s67, 0x2000
	s_nop 0
	global_load_lds_dwordx4 v134, s[68:69]
	s_waitcnt vmcnt(6)
	s_barrier
	s_setprio 1
	v_mfma_f32_16x16x32_bf16 v[50:53], v[210:213], v[172:175], v[50:53]
	ds_read_b128 v[156:159], v151 offset:32768
	v_mfma_f32_16x16x32_bf16 v[42:45], v[218:221], v[172:175], v[42:45]
	ds_read_b128 v[160:163], v151 offset:33792
	v_mfma_f32_16x16x32_bf16 v[34:37], v[210:213], v[180:183], v[34:37]
	ds_read_b128 v[164:167], v151 offset:34816
	v_mfma_f32_16x16x32_bf16 v[26:29], v[218:221], v[180:183], v[26:29]
	ds_read_b128 v[168:171], v151 offset:35840
	v_mfma_f32_16x16x32_bf16 v[18:21], v[210:213], v[188:191], v[18:21]
	v_mfma_f32_16x16x32_bf16 v[10:13], v[218:221], v[188:191], v[10:13]
	v_mfma_f32_16x16x32_bf16 v[6:9], v[210:213], v[202:205], v[6:9]
	v_mfma_f32_16x16x32_bf16 v[2:5], v[218:221], v[202:205], v[2:5]
	v_mfma_f32_16x16x32_bf16 v[50:53], v[214:217], v[176:179], v[50:53]
	v_mfma_f32_16x16x32_bf16 v[42:45], v[222:225], v[176:179], v[42:45]
	v_mfma_f32_16x16x32_bf16 v[34:37], v[214:217], v[184:187], v[34:37]
	v_mfma_f32_16x16x32_bf16 v[26:29], v[222:225], v[184:187], v[26:29]
	v_mfma_f32_16x16x32_bf16 v[18:21], v[214:217], v[192:195], v[18:21]
	v_mfma_f32_16x16x32_bf16 v[10:13], v[222:225], v[192:195], v[10:13]
	v_mfma_f32_16x16x32_bf16 v[6:9], v[214:217], v[206:209], v[6:9]
	v_mfma_f32_16x16x32_bf16 v[2:5], v[222:225], v[206:209], v[2:5]
	s_setprio 0
	s_add_i32 s67, 0, 0x18000
	s_barrier
	s_add_u32 s68, s50, 0x40000
	s_addc_u32 s69, s51, 0
	s_mov_b32 m0, s55
	ds_read_b128 v[172:175], v149 offset:32768
	ds_read_b128 v[176:179], v149 offset:33792
	ds_read_b128 v[180:183], v149 offset:34816
	ds_read_b128 v[184:187], v149 offset:35840
	ds_read_b128 v[188:191], v149 offset:36864
	ds_read_b128 v[192:195], v149 offset:37888
	ds_read_b128 v[202:205], v149 offset:38912
	ds_read_b128 v[206:209], v149 offset:39936
	global_load_lds_dwordx4 v130, s[68:69]
	s_mov_b32 m0, s56
	s_nop 0
	global_load_lds_dwordx4 v132, s[68:69]
	s_waitcnt lgkmcnt(8)
	s_barrier
; #define PG8_STAGE(bufoff, gbase, voff) do { _Pragma("unroll") for (int _i = 0; _i < 2; ++_i) \
;         __builtin_amdgcn_global_load_lds((const unsigned*)((const char*)(gbase) + (voff)[_i]), (LAS unsigned*)(lds + (bufoff) + ldsw + _i * 8192), 16, 0, 0); } while (0)
; #define PG8_LDA(dst, b, h) do { _Pragma("unroll") for (int m = 0; m < 4; ++m) _Pragma("unroll") for (int k = 0; k < 2; ++k) dst[m][k] = *(const LAS bf16x8*)(lds + PG8_SA(b, h) + aoff + m * 2048 + k * 1024); } while (0)
; #define PG8_LDB(dst, b, h) do { _Pragma("unroll") for (int n = 0; n < 2; ++n) _Pragma("unroll") for (int k = 0; k < 2; ++k) dst[n][k] = *(const LAS bf16x8*)(lds + PG8_SB(b, h) + boff + n * 2048 + k * 1024); } while (0)
; #define PG8_MMA(ai, bj, At, Bt) do { __builtin_amdgcn_s_setprio(1); _Pragma("unroll") for (int m = 0; m < 4; ++m) _Pragma("unroll") for (int n = 0; n < 2; ++n) _Pragma("unroll") for (int k = 0; k < 2; ++k) \
;         acc[ai][bj][m][n] = __builtin_amdgcn_mfma_f32_16x16x32_bf16(Bt[n][k], At[m][k], acc[ai][bj][m][n], 0, 0, 0); __builtin_amdgcn_s_setprio(0); } while (0)
; #define PG8_WAIT_V(n) asm volatile("s_waitcnt vmcnt(" #n ")" ::: "memory")
; #define PG8_WAIT_L(n) asm volatile("s_waitcnt lgkmcnt(" #n ")" ::: "memory")
; #define PG8_BAR __builtin_amdgcn_s_barrier()
; #define PG8_SCHED __builtin_amdgcn_sched_barrier(0)
; template <class Epi>
; __device__ __forceinline__ void gemm_phase(LAS unsigned char* lds, const Gemm g, const StaticOrder& S, const Epi& E) {
;     ...
;             PG8_WAIT_L(8); PG8_BAR; PG8_WAIT_L(0); PG8_MMA(0, 0, At, B0); PG8_BAR; PG8_SCHED;
;             PG8_LDB(B1, 1, 1); PG8_STAGE(PG8_SB(1, 0), b3, voffB);
;             PG8_BAR; PG8_WAIT_L(0); PG8_MMA(0, 1, At, B1); PG8_BAR;
;             PG8_LDA(At, 1, 1); PG8_STAGE(PG8_SA(1, 0), a3, voffA);
;             PG8_BAR; PG8_WAIT_L(0); PG8_MMA(1, 0, At, B0); PG8_BAR; PG8_SCHED;
;             PG8_STAGE(PG8_SB(1, 1), b3 + hB, voffB);
;             PG8_WAIT_V(6); PG8_BAR; PG8_MMA(1, 1, At, B1); PG8_BAR;
	s_waitcnt lgkmcnt(0)
	s_setprio 1
	v_mfma_f32_16x16x32_bf16 v[126:129], v[156:159], v[172:175], v[126:129]
	v_mfma_f32_16x16x32_bf16 v[122:125], v[164:167], v[172:175], v[122:125]
	v_mfma_f32_16x16x32_bf16 v[118:121], v[156:159], v[180:183], v[118:121]
	v_mfma_f32_16x16x32_bf16 v[110:113], v[164:167], v[180:183], v[110:113]
	v_mfma_f32_16x16x32_bf16 v[102:105], v[156:159], v[188:191], v[102:105]
	v_mfma_f32_16x16x32_bf16 v[94:97], v[164:167], v[188:191], v[94:97]
	v_mfma_f32_16x16x32_bf16 v[86:89], v[156:159], v[202:205], v[86:89]
	v_mfma_f32_16x16x32_bf16 v[78:81], v[164:167], v[202:205], v[78:81]
	v_mfma_f32_16x16x32_bf16 v[126:129], v[160:163], v[176:179], v[126:129]
	v_mfma_f32_16x16x32_bf16 v[122:125], v[168:171], v[176:179], v[122:125]
	v_mfma_f32_16x16x32_bf16 v[118:121], v[160:163], v[184:187], v[118:121]
	v_mfma_f32_16x16x32_bf16 v[110:113], v[168:171], v[184:187], v[110:113]
	v_mfma_f32_16x16x32_bf16 v[102:105], v[160:163], v[192:195], v[102:105]
	v_mfma_f32_16x16x32_bf16 v[94:97], v[168:171], v[192:195], v[94:97]
	v_mfma_f32_16x16x32_bf16 v[86:89], v[160:163], v[206:209], v[86:89]
	v_mfma_f32_16x16x32_bf16 v[78:81], v[168:171], v[206:209], v[78:81]
	s_setprio 0
	s_barrier
	s_add_i32 s100, 0, 0x1c000
	s_add_i32 s101, s67, s33
	s_add_u32 s68, s48, 0x80
	s_addc_u32 s69, s49, 0
	s_mov_b32 m0, s101
	ds_read_b128 v[210:213], v151 offset:49152
	ds_read_b128 v[214:217], v151 offset:50176
	ds_read_b128 v[218:221], v151 offset:51200
	ds_read_b128 v[222:225], v151 offset:52224
	global_load_lds_dwordx4 v0, s[68:69]
	s_add_i32 m0, s101, 0x2000
	s_nop 0
	global_load_lds_dwordx4 v134, s[68:69]
	s_barrier
	s_waitcnt lgkmcnt(0)
	s_setprio 1
	v_mfma_f32_16x16x32_bf16 v[114:117], v[210:213], v[172:175], v[114:117]
	v_mfma_f32_16x16x32_bf16 v[106:109], v[218:221], v[172:175], v[106:109]
	v_mfma_f32_16x16x32_bf16 v[98:101], v[210:213], v[180:183], v[98:101]
	v_mfma_f32_16x16x32_bf16 v[90:93], v[218:221], v[180:183], v[90:93]
	v_mfma_f32_16x16x32_bf16 v[82:85], v[210:213], v[188:191], v[82:85]
	v_mfma_f32_16x16x32_bf16 v[74:77], v[218:221], v[188:191], v[74:77]
	v_mfma_f32_16x16x32_bf16 v[70:73], v[210:213], v[202:205], v[70:73]
	v_mfma_f32_16x16x32_bf16 v[66:69], v[218:221], v[202:205], v[66:69]
	v_mfma_f32_16x16x32_bf16 v[114:117], v[214:217], v[176:179], v[114:117]
	v_mfma_f32_16x16x32_bf16 v[106:109], v[222:225], v[176:179], v[106:109]
	v_mfma_f32_16x16x32_bf16 v[98:101], v[214:217], v[184:187], v[98:101]
	v_mfma_f32_16x16x32_bf16 v[90:93], v[222:225], v[184:187], v[90:93]
	v_mfma_f32_16x16x32_bf16 v[82:85], v[214:217], v[192:195], v[82:85]
	v_mfma_f32_16x16x32_bf16 v[74:77], v[222:225], v[192:195], v[74:77]
	v_mfma_f32_16x16x32_bf16 v[70:73], v[214:217], v[206:209], v[70:73]
	v_mfma_f32_16x16x32_bf16 v[66:69], v[222:225], v[206:209], v[66:69]
	s_setprio 0
	s_mov_b32 m0, s58
	s_add_u32 s68, s50, 0x80
	s_addc_u32 s69, s51, 0
	s_barrier
	ds_read_b128 v[172:175], v149 offset:49152
	ds_read_b128 v[176:179], v149 offset:50176
	ds_read_b128 v[180:183], v149 offset:51200
	ds_read_b128 v[184:187], v149 offset:52224
	ds_read_b128 v[188:191], v149 offset:53248
	ds_read_b128 v[192:195], v149 offset:54272
	ds_read_b128 v[202:205], v149 offset:55296
	ds_read_b128 v[206:209], v149 offset:56320
	global_load_lds_dwordx4 v130, s[68:69]
	s_mov_b32 m0, s59
	s_nop 0
	global_load_lds_dwordx4 v132, s[68:69]
	s_waitcnt vmcnt(8)
	s_barrier
	s_waitcnt lgkmcnt(0)
	s_setprio 1
	v_mfma_f32_16x16x32_bf16 v[62:65], v[156:159], v[172:175], v[62:65]
	v_mfma_f32_16x16x32_bf16 v[58:61], v[164:167], v[172:175], v[58:61]
	v_mfma_f32_16x16x32_bf16 v[54:57], v[156:159], v[180:183], v[54:57]
	v_mfma_f32_16x16x32_bf16 v[46:49], v[164:167], v[180:183], v[46:49]
	v_mfma_f32_16x16x32_bf16 v[38:41], v[156:159], v[188:191], v[38:41]
	v_mfma_f32_16x16x32_bf16 v[30:33], v[164:167], v[188:191], v[30:33]
	v_mfma_f32_16x16x32_bf16 v[22:25], v[156:159], v[202:205], v[22:25]
	v_mfma_f32_16x16x32_bf16 v[14:17], v[164:167], v[202:205], v[14:17]
	v_mfma_f32_16x16x32_bf16 v[62:65], v[160:163], v[176:179], v[62:65]
	v_mfma_f32_16x16x32_bf16 v[58:61], v[168:171], v[176:179], v[58:61]
	v_mfma_f32_16x16x32_bf16 v[54:57], v[160:163], v[184:187], v[54:57]
	v_mfma_f32_16x16x32_bf16 v[46:49], v[168:171], v[184:187], v[46:49]
	v_mfma_f32_16x16x32_bf16 v[38:41], v[160:163], v[192:195], v[38:41]
	v_mfma_f32_16x16x32_bf16 v[30:33], v[168:171], v[192:195], v[30:33]
	v_mfma_f32_16x16x32_bf16 v[22:25], v[160:163], v[206:209], v[22:25]
	v_mfma_f32_16x16x32_bf16 v[14:17], v[168:171], v[206:209], v[14:17]
	s_setprio 0
	s_barrier
	s_add_u32 s48, s48, 0x40080
	s_addc_u32 s49, s49, 0
	s_add_i32 s100, s100, s33
	s_mov_b32 m0, s100
	s_nop 0
	global_load_lds_dwordx4 v0, s[48:49]
	s_add_i32 m0, s100, 0x2000
	s_nop 0
	global_load_lds_dwordx4 v134, s[48:49]
	s_waitcnt vmcnt(6)
	s_barrier
	s_setprio 1
	v_mfma_f32_16x16x32_bf16 v[50:53], v[210:213], v[172:175], v[50:53]
	ds_read_b128 v[156:159], v151
	v_mfma_f32_16x16x32_bf16 v[42:45], v[218:221], v[172:175], v[42:45]
	ds_read_b128 v[160:163], v151 offset:1024
	v_mfma_f32_16x16x32_bf16 v[34:37], v[210:213], v[180:183], v[34:37]
	ds_read_b128 v[164:167], v151 offset:2048
	v_mfma_f32_16x16x32_bf16 v[26:29], v[218:221], v[180:183], v[26:29]
	ds_read_b128 v[168:171], v151 offset:3072
	v_mfma_f32_16x16x32_bf16 v[18:21], v[210:213], v[188:191], v[18:21]
	v_mfma_f32_16x16x32_bf16 v[10:13], v[218:221], v[188:191], v[10:13]
	v_mfma_f32_16x16x32_bf16 v[6:9], v[210:213], v[202:205], v[6:9]
	v_mfma_f32_16x16x32_bf16 v[2:5], v[218:221], v[202:205], v[2:5]
	v_mfma_f32_16x16x32_bf16 v[50:53], v[214:217], v[176:179], v[50:53]
	v_mfma_f32_16x16x32_bf16 v[42:45], v[222:225], v[176:179], v[42:45]
	v_mfma_f32_16x16x32_bf16 v[34:37], v[214:217], v[184:187], v[34:37]
	v_mfma_f32_16x16x32_bf16 v[26:29], v[222:225], v[184:187], v[26:29]
	v_mfma_f32_16x16x32_bf16 v[18:21], v[214:217], v[192:195], v[18:21]
	v_mfma_f32_16x16x32_bf16 v[10:13], v[222:225], v[192:195], v[10:13]
	v_mfma_f32_16x16x32_bf16 v[6:9], v[214:217], v[206:209], v[6:9]
	v_mfma_f32_16x16x32_bf16 v[2:5], v[222:225], v[206:209], v[2:5]
	s_setprio 0
	s_add_i32 s66, s66, 2
	s_add_u32 s46, s46, 0x100
	s_addc_u32 s47, s47, 0
	s_add_u32 s64, s64, 0x100
	s_addc_u32 s65, s65, 0
	s_cmp_gt_u32 s66, 13
	s_barrier
; __device__ __forceinline__ u32x4 pack8(const f32x4 a, const f32x4 b) { u32x4 w; w.x = cvt_pk_bf16(a[0], a[1]); w.y = cvt_pk_bf16(a[2], a[3]); w.z = cvt_pk_bf16(b[0], b[1]); w.w = cvt_pk_bf16(b[2], b[3]); return w; }
;     __device__ __forceinline__ void operator()(const Acc& acc, const Unit& u, int wr, int wc, int fr, int fq, const RsPre& pr) const {
;         asm volatile("" : "+v"(fr), "+v"(fq));
;         const int row0 = u.pm * 256 + wr * 64 + fr, col0 = u.pn * 256 + wc * 32 + 8 * fq;
;         const float (&rs)[2][4] = pr.rs;
; #pragma unroll
;         for (int ai = 0; ai < 2; ++ai)
; #pragma unroll
;             for (int m = 0; m < 4; ++m) { bf16_t* rowp = O + (size_t)(row0 + ai * 128 + m * 16) * ldc + col0;
; #pragma unroll
;                 for (int bj = 0; bj < 2; ++bj) *(u32x4*)(rowp + bj * 128) = pack8(acc[ai][bj][m][0] * rs[ai][m], acc[ai][bj][m][1] * rs[ai][m]); }
	s_cbranch_scc0 .LBB0_623
	s_waitcnt lgkmcnt(0)
	v_mov_b32_e32 v151, v137
	v_mov_b32_e32 v153, v139
	s_lshl_b32 s15, s44, 8
	s_add_i32 s15, s15, s52
	v_add_u32_e32 v151, s15, v151
	s_lshl_b32 s15, s45, 8
	s_or_b32 s15, s15, s57
	v_lshl_add_u32 v158, v153, 3, s15
	v_lshlrev_b32_e32 v158, 1, v158
	v_mad_u32_u24 v160, v151, s96, v158
	s_waitcnt vmcnt(0)
	v_pk_mul_f32 v[128:129], v[154:155], v[128:129] op_sel_hi:[0,1]
	v_pk_mul_f32 v[126:127], v[154:155], v[126:127] op_sel_hi:[0,1]
	v_pk_mul_f32 v[162:163], v[154:155], v[124:125] op_sel_hi:[0,1]
	v_pk_mul_f32 v[124:125], v[154:155], v[122:123] op_sel_hi:[0,1]
	v_cvt_pk_bf16_f32 v122, v126, v127
	v_cvt_pk_bf16_f32 v123, v128, v129
	v_cvt_pk_bf16_f32 v124, v124, v125
	v_cvt_pk_bf16_f32 v125, v162, v163
	global_store_dwordx4 v160, v[122:125], s[20:21]
	v_pk_mul_f32 v[116:117], v[154:155], v[116:117] op_sel_hi:[0,1]
	v_pk_mul_f32 v[114:115], v[154:155], v[114:115] op_sel_hi:[0,1]
	v_pk_mul_f32 v[122:123], v[154:155], v[108:109] op_sel_hi:[0,1]
	v_pk_mul_f32 v[108:109], v[154:155], v[106:107] op_sel_hi:[0,1]
	v_cvt_pk_bf16_f32 v106, v114, v115
	v_cvt_pk_bf16_f32 v107, v116, v117
	v_cvt_pk_bf16_f32 v108, v108, v109
	v_cvt_pk_bf16_f32 v109, v122, v123
	global_store_dwordx4 v160, v[106:109], s[20:21] offset:256
	v_pk_mul_f32 v[112:113], v[152:153], v[112:113] op_sel_hi:[0,1]
	v_pk_mul_f32 v[110:111], v[152:153], v[110:111] op_sel_hi:[0,1]
	v_add_u32_e32 v114, 0x22000, v160
	v_pk_mul_f32 v[108:109], v[152:153], v[120:121] op_sel_hi:[0,1]
	v_pk_mul_f32 v[106:107], v[152:153], v[118:119] op_sel_hi:[0,1]
	v_cvt_pk_bf16_f32 v106, v106, v107
	v_cvt_pk_bf16_f32 v107, v108, v109
	v_cvt_pk_bf16_f32 v108, v110, v111
	v_cvt_pk_bf16_f32 v109, v112, v113
	global_store_dwordx4 v114, v[106:109], s[20:21]
	v_pk_mul_f32 v[100:101], v[152:153], v[100:101] op_sel_hi:[0,1]
	v_pk_mul_f32 v[98:99], v[152:153], v[98:99] op_sel_hi:[0,1]
	v_pk_mul_f32 v[106:107], v[152:153], v[92:93] op_sel_hi:[0,1]
	v_pk_mul_f32 v[92:93], v[152:153], v[90:91] op_sel_hi:[0,1]
	v_cvt_pk_bf16_f32 v90, v98, v99
	v_cvt_pk_bf16_f32 v91, v100, v101
	v_cvt_pk_bf16_f32 v92, v92, v93
	v_cvt_pk_bf16_f32 v93, v106, v107
	global_store_dwordx4 v114, v[90:93], s[20:21] offset:256
	v_pk_mul_f32 v[96:97], v[150:151], v[96:97] op_sel_hi:[0,1]
	v_pk_mul_f32 v[94:95], v[150:151], v[94:95] op_sel_hi:[0,1]
	v_add_u32_e32 v98, 0x44000, v160
	v_pk_mul_f32 v[92:93], v[150:151], v[104:105] op_sel_hi:[0,1]
	v_pk_mul_f32 v[90:91], v[150:151], v[102:103] op_sel_hi:[0,1]
	v_cvt_pk_bf16_f32 v90, v90, v91
	v_cvt_pk_bf16_f32 v91, v92, v93
	v_cvt_pk_bf16_f32 v92, v94, v95
	v_cvt_pk_bf16_f32 v93, v96, v97
	global_store_dwordx4 v98, v[90:93], s[20:21]
	v_pk_mul_f32 v[84:85], v[150:151], v[84:85] op_sel_hi:[0,1]
	v_pk_mul_f32 v[82:83], v[150:151], v[82:83] op_sel_hi:[0,1]
	v_pk_mul_f32 v[90:91], v[150:151], v[76:77] op_sel_hi:[0,1]
	v_pk_mul_f32 v[76:77], v[150:151], v[74:75] op_sel_hi:[0,1]
	v_cvt_pk_bf16_f32 v74, v82, v83
	v_cvt_pk_bf16_f32 v75, v84, v85
	v_cvt_pk_bf16_f32 v76, v76, v77
	v_cvt_pk_bf16_f32 v77, v90, v91
	global_store_dwordx4 v98, v[74:77], s[20:21] offset:256
	v_pk_mul_f32 v[80:81], v[148:149], v[80:81] op_sel_hi:[0,1]
	v_pk_mul_f32 v[78:79], v[148:149], v[78:79] op_sel_hi:[0,1]
	v_add_u32_e32 v82, 0x66000, v160
	v_pk_mul_f32 v[76:77], v[148:149], v[88:89] op_sel_hi:[0,1]
	v_pk_mul_f32 v[74:75], v[148:149], v[86:87] op_sel_hi:[0,1]
	v_cvt_pk_bf16_f32 v74, v74, v75
	v_cvt_pk_bf16_f32 v75, v76, v77
	v_cvt_pk_bf16_f32 v76, v78, v79
	v_cvt_pk_bf16_f32 v77, v80, v81
	global_store_dwordx4 v82, v[74:77], s[20:21]
	v_pk_mul_f32 v[72:73], v[148:149], v[72:73] op_sel_hi:[0,1]
	v_pk_mul_f32 v[70:71], v[148:149], v[70:71] op_sel_hi:[0,1]
	v_pk_mul_f32 v[74:75], v[148:149], v[68:69] op_sel_hi:[0,1]
	v_pk_mul_f32 v[68:69], v[148:149], v[66:67] op_sel_hi:[0,1]
	v_cvt_pk_bf16_f32 v66, v70, v71
	v_cvt_pk_bf16_f32 v67, v72, v73
	v_cvt_pk_bf16_f32 v68, v68, v69
	v_cvt_pk_bf16_f32 v69, v74, v75
	global_store_dwordx4 v82, v[66:69], s[20:21] offset:256
	v_pk_mul_f32 v[64:65], v[142:143], v[64:65] op_sel_hi:[0,1]
; __device__ __forceinline__ u32x4 pack8(const f32x4 a, const f32x4 b) { u32x4 w; w.x = cvt_pk_bf16(a[0], a[1]); w.y = cvt_pk_bf16(a[2], a[3]); w.z = cvt_pk_bf16(b[0], b[1]); w.w = cvt_pk_bf16(b[2], b[3]); return w; }
;     __device__ __forceinline__ void pre(RsPre& r, const Unit& u, int wr, int fr) const {
; #pragma unroll
;         for (int ai = 0; ai < 2; ++ai)
; #pragma unroll
;             for (int m = 0; m < 4; ++m) r.rs[ai][m] = rsv[u.pm * 256 + wr * 64 + fr + ai * 128 + m * 16]; }
;     __device__ __forceinline__ void operator()(const Acc& acc, const Unit& u, int wr, int wc, int fr, int fq, const RsPre& pr) const {
;     ...
;         for (int ai = 0; ai < 2; ++ai)
; #pragma unroll
;             for (int m = 0; m < 4; ++m) { bf16_t* rowp = O + (size_t)(row0 + ai * 128 + m * 16) * ldc + col0;
; #pragma unroll
;                 for (int bj = 0; bj < 2; ++bj) *(u32x4*)(rowp + bj * 128) = pack8(acc[ai][bj][m][0] * rs[ai][m], acc[ai][bj][m][1] * rs[ai][m]); }
	v_pk_mul_f32 v[62:63], v[142:143], v[62:63] op_sel_hi:[0,1]
	v_pk_mul_f32 v[68:69], v[142:143], v[60:61] op_sel_hi:[0,1]
	v_pk_mul_f32 v[60:61], v[142:143], v[58:59] op_sel_hi:[0,1]
	v_add_u32_e32 v66, 0x110000, v160
	v_cvt_pk_bf16_f32 v58, v62, v63
	v_cvt_pk_bf16_f32 v59, v64, v65
	v_cvt_pk_bf16_f32 v60, v60, v61
	v_cvt_pk_bf16_f32 v61, v68, v69
	global_store_dwordx4 v66, v[58:61], s[20:21]
	v_pk_mul_f32 v[52:53], v[142:143], v[52:53] op_sel_hi:[0,1]
	v_pk_mul_f32 v[50:51], v[142:143], v[50:51] op_sel_hi:[0,1]
	v_pk_mul_f32 v[58:59], v[142:143], v[44:45] op_sel_hi:[0,1]
	v_pk_mul_f32 v[44:45], v[142:143], v[42:43] op_sel_hi:[0,1]
	v_cvt_pk_bf16_f32 v42, v50, v51
	v_cvt_pk_bf16_f32 v43, v52, v53
	v_cvt_pk_bf16_f32 v44, v44, v45
	v_cvt_pk_bf16_f32 v45, v58, v59
	global_store_dwordx4 v66, v[42:45], s[20:21] offset:256
	v_pk_mul_f32 v[48:49], v[140:141], v[48:49] op_sel_hi:[0,1]
	v_pk_mul_f32 v[46:47], v[140:141], v[46:47] op_sel_hi:[0,1]
	v_add_u32_e32 v50, 0x132000, v160
	v_pk_mul_f32 v[44:45], v[140:141], v[56:57] op_sel_hi:[0,1]
	v_pk_mul_f32 v[42:43], v[140:141], v[54:55] op_sel_hi:[0,1]
	v_cvt_pk_bf16_f32 v42, v42, v43
	v_cvt_pk_bf16_f32 v43, v44, v45
	v_cvt_pk_bf16_f32 v44, v46, v47
	v_cvt_pk_bf16_f32 v45, v48, v49
	global_store_dwordx4 v50, v[42:45], s[20:21]
	v_pk_mul_f32 v[36:37], v[140:141], v[36:37] op_sel_hi:[0,1]
	v_pk_mul_f32 v[34:35], v[140:141], v[34:35] op_sel_hi:[0,1]
	v_pk_mul_f32 v[42:43], v[140:141], v[28:29] op_sel_hi:[0,1]
	v_pk_mul_f32 v[28:29], v[140:141], v[26:27] op_sel_hi:[0,1]
	v_cvt_pk_bf16_f32 v26, v34, v35
	v_cvt_pk_bf16_f32 v27, v36, v37
	v_cvt_pk_bf16_f32 v28, v28, v29
	v_cvt_pk_bf16_f32 v29, v42, v43
	global_store_dwordx4 v50, v[26:29], s[20:21] offset:256
	v_pk_mul_f32 v[32:33], v[138:139], v[32:33] op_sel_hi:[0,1]
	v_pk_mul_f32 v[30:31], v[138:139], v[30:31] op_sel_hi:[0,1]
	v_add_u32_e32 v34, 0x154000, v160
	v_pk_mul_f32 v[28:29], v[138:139], v[40:41] op_sel_hi:[0,1]
	v_pk_mul_f32 v[26:27], v[138:139], v[38:39] op_sel_hi:[0,1]
	v_cvt_pk_bf16_f32 v26, v26, v27
	v_cvt_pk_bf16_f32 v27, v28, v29
	v_cvt_pk_bf16_f32 v28, v30, v31
	v_cvt_pk_bf16_f32 v29, v32, v33
	global_store_dwordx4 v34, v[26:29], s[20:21]
	v_pk_mul_f32 v[20:21], v[138:139], v[20:21] op_sel_hi:[0,1]
	v_pk_mul_f32 v[18:19], v[138:139], v[18:19] op_sel_hi:[0,1]
	v_pk_mul_f32 v[26:27], v[138:139], v[12:13] op_sel_hi:[0,1]
	v_pk_mul_f32 v[12:13], v[138:139], v[10:11] op_sel_hi:[0,1]
	v_cvt_pk_bf16_f32 v10, v18, v19
	v_cvt_pk_bf16_f32 v11, v20, v21
	v_cvt_pk_bf16_f32 v12, v12, v13
	v_cvt_pk_bf16_f32 v13, v26, v27
	global_store_dwordx4 v34, v[10:13], s[20:21] offset:256
	v_pk_mul_f32 v[16:17], v[136:137], v[16:17] op_sel_hi:[0,1]
	v_pk_mul_f32 v[14:15], v[136:137], v[14:15] op_sel_hi:[0,1]
	v_add_u32_e32 v18, 0x176000, v160
	v_pk_mul_f32 v[12:13], v[136:137], v[24:25] op_sel_hi:[0,1]
	v_pk_mul_f32 v[10:11], v[136:137], v[22:23] op_sel_hi:[0,1]
	v_cvt_pk_bf16_f32 v10, v10, v11
	v_cvt_pk_bf16_f32 v11, v12, v13
	v_cvt_pk_bf16_f32 v12, v14, v15
	v_cvt_pk_bf16_f32 v13, v16, v17
	global_store_dwordx4 v18, v[10:13], s[20:21]
	v_pk_mul_f32 v[8:9], v[136:137], v[8:9] op_sel_hi:[0,1]
	v_pk_mul_f32 v[6:7], v[136:137], v[6:7] op_sel_hi:[0,1]
	v_pk_mul_f32 v[10:11], v[136:137], v[4:5] op_sel_hi:[0,1]
	v_pk_mul_f32 v[4:5], v[136:137], v[2:3] op_sel_hi:[0,1]
	v_cvt_pk_bf16_f32 v2, v6, v7
	v_cvt_pk_bf16_f32 v3, v8, v9
	v_cvt_pk_bf16_f32 v4, v4, v5
	v_cvt_pk_bf16_f32 v5, v10, v11
	s_mov_b64 s[44:45], -1
	s_and_b64 vcc, vcc, exec
	global_store_dwordx4 v18, v[2:5], s[20:21] offset:256
	s_cbranch_vccz .LBB0_615
	s_nop 0
	v_lshl_add_u32 v2, s22, 8, v141
	v_ashrrev_i32_e32 v3, 31, v2
	v_lshl_add_u64 v[2:3], v[2:3], 2, s[10:11]
	global_load_dword v154, v[2:3], off
	global_load_dword v152, v[2:3], off offset:64
	global_load_dword v150, v[2:3], off offset:128
	global_load_dword v148, v[2:3], off offset:192
	global_load_dword v142, v[2:3], off offset:512
	global_load_dword v140, v[2:3], off offset:576
	global_load_dword v138, v[2:3], off offset:640
	global_load_dword v136, v[2:3], off offset:704
	s_mov_b64 s[44:45], 0
	s_branch .LBB0_615
